# in_proj epilogue rope tiles: each row block's rope-table loads are issued one block ahead (global loads into a spare buffer, counted wait vmcnt(1)); epilogue flat stores -> global stores
# speedup vs baseline: 1.0073x; 1.0073x over previous
;     __device__ __forceinline__ void operator()(const f32x4 (&acc)[2][2][4][2], const pg8::Unit& u, int wr, int wc, int fr, int fq, LAS unsigned char* lds, int par) const {
;     ...
;                         const int pos = row & (SEQ - 1), i0 = (c & 63) >> 1;
;                         const f32x4 r0 = *(const f32x4*)(rope + ((size_t)pos * 32 + i0) * 2), r1 = *(const f32x4*)(rope + ((size_t)pos * 32 + i0 + 2) * 2);
;                         const float sc = (kind == 1) ? 0.125f : 1.0f;
;                         f32x4 o0, o1;
;                         o0[0] = (v0[0] * r0[0] - v0[1] * r0[1]) * sc; o0[1] = (v0[1] * r0[0] + v0[0] * r0[1]) * sc;
;                         o0[2] = (v0[2] * r0[2] - v0[3] * r0[3]) * sc; o0[3] = (v0[3] * r0[2] + v0[2] * r0[3]) * sc;
;                         o1[0] = (v1[0] * r1[0] - v1[1] * r1[1]) * sc; o1[1] = (v1[1] * r1[0] + v1[0] * r1[1]) * sc;
;                         o1[2] = (v1[2] * r1[2] - v1[3] * r1[3]) * sc; o1[3] = (v1[3] * r1[2] + v1[2] * r1[3]) * sc;
;                         v0 = o0; v1 = o1;
.LBB0_578:
	s_andn2_b64 vcc, exec, s[50:51]
	s_cbranch_vccnz .LBB0_580
	v_lshl_or_b32 v0, v187, 3, v168
	v_lshl_add_u64 v[160:161], s[12:13], 0, v[0:1]
	flat_load_dwordx4 v[156:159], v[160:161]
	s_nop 0
	flat_load_dwordx4 v[160:163], v[160:161] offset:16
	s_waitcnt vmcnt(0) lgkmcnt(0)
	v_or_b32_e32 v246, v187, v178
	v_lshlrev_b32_e32 v246, 3, v246
	global_load_dwordx4 v[228:231], v246, s[12:13]
	global_load_dwordx4 v[232:235], v246, s[12:13] offset:16
	v_pk_mul_f32 v[172:173], v[126:127], v[156:157] op_sel:[1,1] op_sel_hi:[0,1]
	v_mul_f32_e32 v0, v129, v159
	v_pk_fma_f32 v[174:175], v[126:127], v[156:157], v[172:173] neg_lo:[0,0,1] neg_hi:[0,0,1]
	v_pk_fma_f32 v[156:157], v[126:127], v[156:157], v[172:173] op_sel_hi:[1,0,1]
	v_pk_fma_f32 v[172:173], v[128:129], v[158:159], v[0:1] op_sel_hi:[1,1,0] neg_lo:[0,0,1] neg_hi:[0,0,1]
	v_mul_f32_e32 v0, v129, v158
	v_pk_fma_f32 v[158:159], v[128:129], v[158:159], v[0:1] op_sel:[1,0,0] op_sel_hi:[0,1,0]
	v_mov_b32_e32 v173, v159
	v_mov_b32_e32 v175, v157
	v_pk_mul_f32 v[158:159], v[148:149], v[172:173] op_sel_hi:[0,1]
	v_pk_mul_f32 v[172:173], v[122:123], v[160:161] op_sel:[1,1] op_sel_hi:[0,1]
	v_mul_f32_e32 v0, v125, v163
	v_pk_mul_f32 v[156:157], v[148:149], v[174:175] op_sel_hi:[0,1]
	v_pk_fma_f32 v[174:175], v[122:123], v[160:161], v[172:173] neg_lo:[0,0,1] neg_hi:[0,0,1]
	v_pk_fma_f32 v[160:161], v[122:123], v[160:161], v[172:173] op_sel_hi:[1,0,1]
	v_pk_fma_f32 v[172:173], v[124:125], v[162:163], v[0:1] op_sel_hi:[1,1,0] neg_lo:[0,0,1] neg_hi:[0,0,1]
	v_mul_f32_e32 v0, v125, v162
	v_pk_fma_f32 v[162:163], v[124:125], v[162:163], v[0:1] op_sel:[1,0,0] op_sel_hi:[0,1,0]
	v_mov_b32_e32 v175, v161
	v_mov_b32_e32 v173, v163
	v_pk_mul_f32 v[160:161], v[148:149], v[174:175] op_sel_hi:[0,1]
	v_pk_mul_f32 v[162:163], v[148:149], v[172:173] op_sel_hi:[0,1]

; __device__ __forceinline__ float bf_lo(unsigned w) { return __uint_as_float(w << 16); }
; __device__ __forceinline__ float bf_hi(unsigned w) { return __uint_as_float(w & 0xffff0000u); }
; __device__ __forceinline__ u32x4 pack8(const f32x4 a, const f32x4 b) { u32x4 w; w.x = cvt_pk_bf16(a[0], a[1]); w.y = cvt_pk_bf16(a[2], a[3]); w.z = cvt_pk_bf16(b[0], b[1]); w.w = cvt_pk_bf16(b[2], b[3]); return w; }
;     __device__ __forceinline__ void operator()(const f32x4 (&acc)[2][2][4][2], const pg8::Unit& u, int wr, int wc, int fr, int fq, LAS unsigned char* lds, int par) const {
;     ...
;                     const u32x4 pw = pack8(v0, v1);
;                     *(u32x4*)(base + (size_t)row * ld + ct + c) = pw;
;                     if (kind == 0 && pn >= 4) {
;                         const float a0 = bf_lo(pw.x), a1 = bf_hi(pw.x), a2 = bf_lo(pw.y), a3 = bf_hi(pw.y), a4 = bf_lo(pw.z), a5 = bf_hi(pw.z), a6 = bf_lo(pw.w), a7 = bf_hi(pw.w);
;                         s1 += ((a0 + a1) + (a2 + a3)) + ((a4 + a5) + (a6 + a7));
;                         s2 += ((a0 * a0 + a1 * a1) + (a2 * a2 + a3 * a3)) + ((a4 * a4 + a5 * a5) + (a6 * a6 + a7 * a7));
;                     }
.LBB0_583:
	s_ashr_i32 s35, s34, 31
	s_lshl_b64 s[34:35], s[34:35], 1
	s_add_u32 s34, s38, s34
	s_addc_u32 s35, s39, s35
	v_ashrrev_i32_e32 v151, 31, v150
	v_mad_u64_u32 v[122:123], s[38:39], s28, v150, 0
	s_cmp_gt_i32 s36, 3
	v_mul_lo_u32 v0, s29, v150
	v_mul_lo_u32 v124, s28, v151
	s_cselect_b64 s[38:39], -1, 0
	v_add3_u32 v123, v123, v124, v0
	s_and_b64 s[38:39], s[38:39], s[46:47]
	v_lshl_add_u64 v[126:127], v[122:123], 1, s[34:35]
	v_lshlrev_b32_e32 v0, 1, v138
	v_cndmask_b32_e64 v129, 0, 1, s[38:39]
	v_lshl_add_u64 v[126:127], v[126:127], 0, v[0:1]
	v_mov_b32_e32 v128, 0
	v_cmp_ne_u32_e64 s[46:47], 1, v129
	s_andn2_b64 vcc, exec, s[38:39]
	v_mov_b32_e32 v129, 0
	v_cvt_pk_bf16_f32 v122, v156, v157
	v_cvt_pk_bf16_f32 v123, v158, v159
	v_cvt_pk_bf16_f32 v124, v160, v161
	v_cvt_pk_bf16_f32 v125, v162, v163
	global_store_dwordx4 v[126:127], v[122:125], off
	s_cbranch_vccnz .LBB0_585
	v_and_b32_e32 v129, 16, v122
	v_and_b32_e32 v128, 0xffff0000, v122
	v_lshlrev_b32_e32 v159, 16, v123
	v_lshlrev_b32_e32 v158, 16, v124
	v_and_b32_e32 v156, 0xffff0000, v123
	v_mov_b32_e32 v157, v128
	v_pk_mov_b32 v[172:173], v[158:159], v[128:129] op_sel:[1,0]
	v_lshlrev_b32_e32 v122, 16, v122
	v_and_b32_e32 v160, 0xffff0000, v125
	v_mov_b32_e32 v161, v156
	v_and_b32_e32 v124, 0xffff0000, v124
	v_lshlrev_b32_e32 v162, 16, v125
	v_mov_b32_e32 v125, v159
	v_mov_b32_e32 v123, v156
	v_mov_b32_e32 v163, v156
	v_pk_add_f32 v[174:175], v[156:157], v[172:173]
	v_pk_mul_f32 v[156:157], v[156:157], v[172:173]
	v_pk_add_f32 v[128:129], v[122:123], v[128:129] op_sel_hi:[0,1]
	v_mov_b32_e32 v175, v157
	v_pk_add_f32 v[156:157], v[158:159], v[124:125]
	v_pk_mul_f32 v[172:173], v[158:159], v[158:159]
	v_mov_b32_e32 v125, v160
	v_mul_f32_e32 v129, v122, v122
	v_mov_b32_e32 v157, v173
	v_pk_add_f32 v[172:173], v[160:161], v[162:163]
	v_pk_mul_f32 v[122:123], v[160:161], v[122:123]
	v_mov_b32_e32 v159, v162
	v_pk_mul_f32 v[124:125], v[124:125], v[124:125]
	v_mov_b32_e32 v173, v123
	v_pk_fma_f32 v[124:125], v[158:159], v[158:159], v[124:125]
	v_pk_add_f32 v[128:129], v[128:129], v[174:175]
	v_pk_add_f32 v[122:123], v[156:157], v[172:173]
	v_pk_add_f32 v[124:125], v[124:125], v[124:125] op_sel_hi:[0,1]
	v_pk_add_f32 v[122:123], v[128:129], v[122:123]
	v_mov_b32_e32 v124, v1
	v_pk_add_f32 v[128:129], v[122:123], v[124:125]

;     __device__ __forceinline__ void operator()(const f32x4 (&acc)[2][2][4][2], const pg8::Unit& u, int wr, int wc, int fr, int fq, LAS unsigned char* lds, int par) const {
;     ...
;                         const int pos = row & (SEQ - 1), i0 = (c & 63) >> 1;
;                         const f32x4 r0 = *(const f32x4*)(rope + ((size_t)pos * 32 + i0) * 2), r1 = *(const f32x4*)(rope + ((size_t)pos * 32 + i0 + 2) * 2);
;                         const float sc = (kind == 1) ? 0.125f : 1.0f;
;                         f32x4 o0, o1;
;                         o0[0] = (v0[0] * r0[0] - v0[1] * r0[1]) * sc; o0[1] = (v0[1] * r0[0] + v0[0] * r0[1]) * sc;
;                         o0[2] = (v0[2] * r0[2] - v0[3] * r0[3]) * sc; o0[3] = (v0[3] * r0[2] + v0[2] * r0[3]) * sc;
;                         o1[0] = (v1[0] * r1[0] - v1[1] * r1[1]) * sc; o1[1] = (v1[1] * r1[0] + v1[0] * r1[1]) * sc;
;                         o1[2] = (v1[2] * r1[2] - v1[3] * r1[3]) * sc; o1[3] = (v1[3] * r1[2] + v1[2] * r1[3]) * sc;
;                         v0 = o0; v1 = o1;
.LBB0_592:
	s_andn2_b64 vcc, exec, s[38:39]
	s_cbranch_vccnz .LBB0_594
	s_waitcnt vmcnt(1) lgkmcnt(0)
	v_mov_b32_e32 v122, v228
	v_mov_b32_e32 v123, v229
	v_mov_b32_e32 v124, v230
	v_mov_b32_e32 v125, v231
	v_mov_b32_e32 v152, v232
	v_mov_b32_e32 v153, v233
	v_mov_b32_e32 v154, v234
	v_mov_b32_e32 v155, v235
	v_or_b32_e32 v246, 16, v150
	v_lshlrev_b32_e32 v246, 5, v246
	v_and_b32_e32 v246, 0x1fbe0, v246
	v_lshl_or_b32 v246, v246, 3, v168
	global_load_dwordx4 v[228:231], v246, s[12:13]
	global_load_dwordx4 v[232:235], v246, s[12:13] offset:16
	v_pk_mul_f32 v[158:159], v[118:119], v[122:123] op_sel:[1,1] op_sel_hi:[0,1]
	v_pk_fma_f32 v[160:161], v[118:119], v[122:123], v[158:159] neg_lo:[0,0,1] neg_hi:[0,0,1]
	v_pk_fma_f32 v[122:123], v[118:119], v[122:123], v[158:159] op_sel_hi:[1,0,1]
	v_mul_f32_e32 v158, v121, v125
	v_mov_b32_e32 v161, v123
	v_pk_mul_f32 v[122:123], v[148:149], v[160:161] op_sel_hi:[0,1]
	v_mul_f32_e32 v160, v121, v124
	v_pk_fma_f32 v[158:159], v[120:121], v[124:125], v[158:159] op_sel_hi:[1,1,0] neg_lo:[0,0,1] neg_hi:[0,0,1]
	v_pk_fma_f32 v[124:125], v[120:121], v[124:125], v[160:161] op_sel:[1,0,0] op_sel_hi:[0,1,0]
	v_mov_b32_e32 v159, v125
	v_pk_mul_f32 v[124:125], v[148:149], v[158:159] op_sel_hi:[0,1]
	v_pk_mul_f32 v[158:159], v[114:115], v[152:153] op_sel:[1,1] op_sel_hi:[0,1]
	v_pk_fma_f32 v[160:161], v[114:115], v[152:153], v[158:159] neg_lo:[0,0,1] neg_hi:[0,0,1]
	v_pk_fma_f32 v[152:153], v[114:115], v[152:153], v[158:159] op_sel_hi:[1,0,1]
	v_mul_f32_e32 v158, v117, v155
	v_mov_b32_e32 v161, v153
	v_pk_mul_f32 v[152:153], v[148:149], v[160:161] op_sel_hi:[0,1]
	v_mul_f32_e32 v160, v117, v154
	v_pk_fma_f32 v[158:159], v[116:117], v[154:155], v[158:159] op_sel_hi:[1,1,0] neg_lo:[0,0,1] neg_hi:[0,0,1]
	v_pk_fma_f32 v[154:155], v[116:117], v[154:155], v[160:161] op_sel:[1,0,0] op_sel_hi:[0,1,0]
	v_mov_b32_e32 v159, v155
	v_pk_mul_f32 v[154:155], v[148:149], v[158:159] op_sel_hi:[0,1]

; __device__ __forceinline__ float bf_lo(unsigned w) { return __uint_as_float(w << 16); }
; __device__ __forceinline__ float bf_hi(unsigned w) { return __uint_as_float(w & 0xffff0000u); }
; __device__ __forceinline__ float shflx(float v, int k, int lane) { return __int_as_float(__builtin_amdgcn_ds_bpermute((lane ^ k) << 2, __float_as_int(v))); }
; __device__ __forceinline__ u32x4 pack8(const f32x4 a, const f32x4 b) { u32x4 w; w.x = cvt_pk_bf16(a[0], a[1]); w.y = cvt_pk_bf16(a[2], a[3]); w.z = cvt_pk_bf16(b[0], b[1]); w.w = cvt_pk_bf16(b[2], b[3]); return w; }
;     __device__ __forceinline__ void operator()(const f32x4 (&acc)[2][2][4][2], const pg8::Unit& u, int wr, int wc, int fr, int fq, LAS unsigned char* lds, int par) const {
;     ...
;                     const u32x4 pw = pack8(v0, v1);
;                     *(u32x4*)(base + (size_t)row * ld + ct + c) = pw;
;                     if (kind == 0 && pn >= 4) {
;                         const float a0 = bf_lo(pw.x), a1 = bf_hi(pw.x), a2 = bf_lo(pw.y), a3 = bf_hi(pw.y), a4 = bf_lo(pw.z), a5 = bf_hi(pw.z), a6 = bf_lo(pw.w), a7 = bf_hi(pw.w);
;                         s1 += ((a0 + a1) + (a2 + a3)) + ((a4 + a5) + (a6 + a7));
;                         s2 += ((a0 * a0 + a1 * a1) + (a2 * a2 + a3 * a3)) + ((a4 * a4 + a5 * a5) + (a6 * a6 + a7 * a7));
;                     }
;                 }
;                 if (kind == 0 && pn >= 4) {
;                     s1 += shflx(s1, 16, fr + 16 * fq); s1 += shflx(s1, 32, fr + 16 * fq); s2 += shflx(s2, 16, fr + 16 * fq); s2 += shflx(s2, 32, fr + 16 * fq);
;                     if (fq == 0) { float* sp = statsv + ((size_t)row * 16 + (pn - 4) * 4 + wc) * 2; sp[0] = s1; sp[1] = s2; }
.LBB0_597:
	s_lshl_b32 s2, s36, 2
	s_add_i32 s2, s63, s2
	s_and_b64 vcc, exec, s[46:47]
	v_cvt_pk_bf16_f32 v114, v122, v123
	v_cvt_pk_bf16_f32 v115, v124, v125
	v_cvt_pk_bf16_f32 v116, v152, v153
	v_cvt_pk_bf16_f32 v117, v154, v155
	global_store_dwordx4 v[126:127], v[114:117], off offset:16
	s_cbranch_vccnz .LBB0_601
	v_lshlrev_b32_e32 v118, 16, v114
	v_and_b32_e32 v114, 0xffff0000, v114
	v_lshlrev_b32_e32 v120, 16, v115
	v_and_b32_e32 v122, 0xffff0000, v115
	v_lshlrev_b32_e32 v124, 16, v116
	v_and_b32_e32 v116, 0xffff0000, v116
	v_lshlrev_b32_e32 v126, 16, v117
	v_and_b32_e32 v152, 0xffff0000, v117
	v_mul_f32_e32 v119, v118, v118
	v_mul_f32_e32 v115, v114, v114
	v_mul_f32_e32 v121, v120, v120
	v_mul_f32_e32 v123, v122, v122
	v_mul_f32_e32 v125, v124, v124
	v_mul_f32_e32 v117, v116, v116
	v_mul_f32_e32 v127, v126, v126
	v_mul_f32_e32 v153, v152, v152
	v_pk_add_f32 v[114:115], v[118:119], v[114:115]
	v_pk_add_f32 v[118:119], v[120:121], v[122:123]
	v_pk_add_f32 v[116:117], v[124:125], v[116:117]
	v_pk_add_f32 v[114:115], v[114:115], v[118:119]
	v_pk_add_f32 v[118:119], v[126:127], v[152:153]
	s_nop 0
	v_pk_add_f32 v[116:117], v[116:117], v[118:119]
	s_nop 0
	v_pk_add_f32 v[114:115], v[114:115], v[116:117]
	s_nop 0
	v_pk_add_f32 v[114:115], v[128:129], v[114:115]
	ds_bpermute_b32 v116, v164, v114
	ds_bpermute_b32 v117, v164, v115
	s_waitcnt lgkmcnt(0)
	v_pk_add_f32 v[114:115], v[114:115], v[116:117]
	ds_bpermute_b32 v116, v165, v114
	ds_bpermute_b32 v117, v165, v115
	s_and_saveexec_b64 s[36:37], s[40:41]
	s_cbranch_execz .LBB0_600
	v_readlane_b32 s38, v252, 6
	v_lshlrev_b64 v[118:119], 7, v[150:151]
	v_readlane_b32 s39, v252, 7
	s_waitcnt lgkmcnt(0)
	v_pk_add_f32 v[114:115], v[114:115], v[116:117]
	v_lshl_add_u64 v[118:119], s[38:39], 0, v[118:119]
	v_lshl_add_u64 v[118:119], s[2:3], 3, v[118:119]
	global_store_dwordx2 v[118:119], v[114:115], off

;     __device__ __forceinline__ void operator()(const f32x4 (&acc)[2][2][4][2], const pg8::Unit& u, int wr, int wc, int fr, int fq, LAS unsigned char* lds, int par) const {
;     ...
;                         const int pos = row & (SEQ - 1), i0 = (c & 63) >> 1;
;                         const f32x4 r0 = *(const f32x4*)(rope + ((size_t)pos * 32 + i0) * 2), r1 = *(const f32x4*)(rope + ((size_t)pos * 32 + i0 + 2) * 2);
;                         const float sc = (kind == 1) ? 0.125f : 1.0f;
;                         f32x4 o0, o1;
;                         o0[0] = (v0[0] * r0[0] - v0[1] * r0[1]) * sc; o0[1] = (v0[1] * r0[0] + v0[0] * r0[1]) * sc;
;                         o0[2] = (v0[2] * r0[2] - v0[3] * r0[3]) * sc; o0[3] = (v0[3] * r0[2] + v0[2] * r0[3]) * sc;
;                         o1[0] = (v1[0] * r1[0] - v1[1] * r1[1]) * sc; o1[1] = (v1[1] * r1[0] + v1[0] * r1[1]) * sc;
;                         o1[2] = (v1[2] * r1[2] - v1[3] * r1[3]) * sc; o1[3] = (v1[3] * r1[2] + v1[2] * r1[3]) * sc;
;                         v0 = o0; v1 = o1;
.LBB0_610:
	s_andn2_b64 vcc, exec, s[36:37]
	s_cbranch_vccnz .LBB0_612
	s_waitcnt vmcnt(1) lgkmcnt(0)
	v_mov_b32_e32 v120, v228
	v_mov_b32_e32 v121, v229
	v_mov_b32_e32 v122, v230
	v_mov_b32_e32 v123, v231
	v_mov_b32_e32 v124, v232
	v_mov_b32_e32 v125, v233
	v_mov_b32_e32 v126, v234
	v_mov_b32_e32 v127, v235
	v_or_b32_e32 v246, v128, v178
	v_lshlrev_b32_e32 v246, 3, v246
	global_load_dwordx4 v[228:231], v246, s[12:13]
	global_load_dwordx4 v[232:235], v246, s[12:13] offset:16
	v_pk_mul_f32 v[152:153], v[110:111], v[120:121] op_sel:[1,1] op_sel_hi:[0,1]
	v_pk_fma_f32 v[154:155], v[110:111], v[120:121], v[152:153] neg_lo:[0,0,1] neg_hi:[0,0,1]
	v_pk_fma_f32 v[120:121], v[110:111], v[120:121], v[152:153] op_sel_hi:[1,0,1]
	v_mul_f32_e32 v152, v113, v123
	v_mov_b32_e32 v155, v121
	v_pk_mul_f32 v[120:121], v[148:149], v[154:155] op_sel_hi:[0,1]
	v_mul_f32_e32 v154, v113, v122
	v_pk_fma_f32 v[152:153], v[112:113], v[122:123], v[152:153] op_sel_hi:[1,1,0] neg_lo:[0,0,1] neg_hi:[0,0,1]
	v_pk_fma_f32 v[122:123], v[112:113], v[122:123], v[154:155] op_sel:[1,0,0] op_sel_hi:[0,1,0]
	v_mov_b32_e32 v153, v123
	v_pk_mul_f32 v[122:123], v[148:149], v[152:153] op_sel_hi:[0,1]
	v_pk_mul_f32 v[152:153], v[106:107], v[124:125] op_sel:[1,1] op_sel_hi:[0,1]
	v_pk_fma_f32 v[154:155], v[106:107], v[124:125], v[152:153] neg_lo:[0,0,1] neg_hi:[0,0,1]
	v_pk_fma_f32 v[124:125], v[106:107], v[124:125], v[152:153] op_sel_hi:[1,0,1]
	v_mul_f32_e32 v152, v109, v127
	v_mov_b32_e32 v155, v125
	v_pk_mul_f32 v[124:125], v[148:149], v[154:155] op_sel_hi:[0,1]
	v_mul_f32_e32 v154, v109, v126
	v_pk_fma_f32 v[152:153], v[108:109], v[126:127], v[152:153] op_sel_hi:[1,1,0] neg_lo:[0,0,1] neg_hi:[0,0,1]
	v_pk_fma_f32 v[126:127], v[108:109], v[126:127], v[154:155] op_sel:[1,0,0] op_sel_hi:[0,1,0]
	v_mov_b32_e32 v153, v127
	v_pk_mul_f32 v[126:127], v[148:149], v[152:153] op_sel_hi:[0,1]

; __device__ __forceinline__ float bf_lo(unsigned w) { return __uint_as_float(w << 16); }
; __device__ __forceinline__ float bf_hi(unsigned w) { return __uint_as_float(w & 0xffff0000u); }
; __device__ __forceinline__ u32x4 pack8(const f32x4 a, const f32x4 b) { u32x4 w; w.x = cvt_pk_bf16(a[0], a[1]); w.y = cvt_pk_bf16(a[2], a[3]); w.z = cvt_pk_bf16(b[0], b[1]); w.w = cvt_pk_bf16(b[2], b[3]); return w; }
;     __device__ __forceinline__ void operator()(const f32x4 (&acc)[2][2][4][2], const pg8::Unit& u, int wr, int wc, int fr, int fq, LAS unsigned char* lds, int par) const {
;     ...
;                     const u32x4 pw = pack8(v0, v1);
;                     *(u32x4*)(base + (size_t)row * ld + ct + c) = pw;
;                     if (kind == 0 && pn >= 4) {
;                         const float a0 = bf_lo(pw.x), a1 = bf_hi(pw.x), a2 = bf_lo(pw.y), a3 = bf_hi(pw.y), a4 = bf_lo(pw.z), a5 = bf_hi(pw.z), a6 = bf_lo(pw.w), a7 = bf_hi(pw.w);
;                         s1 += ((a0 + a1) + (a2 + a3)) + ((a4 + a5) + (a6 + a7));
;                         s2 += ((a0 * a0 + a1 * a1) + (a2 * a2 + a3 * a3)) + ((a4 * a4 + a5 * a5) + (a6 * a6 + a7 * a7));
;                     }
.LBB0_615:
	v_ashrrev_i32_e32 v115, 31, v114
	v_mul_lo_u32 v108, s29, v114
	v_mul_lo_u32 v109, s28, v115
	v_mad_u64_u32 v[106:107], s[36:37], s28, v114, 0
	v_add3_u32 v107, v107, v109, v108
	v_lshl_add_u64 v[110:111], v[106:107], 1, s[34:35]
	v_lshl_add_u64 v[110:111], v[110:111], 0, v[0:1]
	v_mov_b32_e32 v112, 0
	s_and_b64 vcc, exec, s[46:47]
	v_mov_b32_e32 v113, 0
	v_cvt_pk_bf16_f32 v106, v120, v121
	v_cvt_pk_bf16_f32 v107, v122, v123
	v_cvt_pk_bf16_f32 v108, v124, v125
	v_cvt_pk_bf16_f32 v109, v126, v127
	global_store_dwordx4 v[110:111], v[106:109], off
	s_cbranch_vccnz .LBB0_617
	v_and_b32_e32 v113, 16, v106
	v_and_b32_e32 v112, 0xffff0000, v106
	v_lshlrev_b32_e32 v123, 16, v107
	v_lshlrev_b32_e32 v122, 16, v108
	v_and_b32_e32 v120, 0xffff0000, v107
	v_mov_b32_e32 v121, v112
	v_pk_mov_b32 v[152:153], v[122:123], v[112:113] op_sel:[1,0]
	v_lshlrev_b32_e32 v106, 16, v106
	v_and_b32_e32 v124, 0xffff0000, v109
	v_mov_b32_e32 v125, v120
	v_and_b32_e32 v108, 0xffff0000, v108
	v_lshlrev_b32_e32 v126, 16, v109
	v_mov_b32_e32 v109, v123
	v_mov_b32_e32 v107, v120
	v_mov_b32_e32 v127, v120
	v_pk_add_f32 v[154:155], v[120:121], v[152:153]
	v_pk_mul_f32 v[120:121], v[120:121], v[152:153]
	v_pk_add_f32 v[112:113], v[106:107], v[112:113] op_sel_hi:[0,1]
	v_mov_b32_e32 v155, v121
	v_pk_add_f32 v[120:121], v[122:123], v[108:109]
	v_pk_mul_f32 v[152:153], v[122:123], v[122:123]
	v_mov_b32_e32 v109, v124
	v_mul_f32_e32 v113, v106, v106
	v_mov_b32_e32 v121, v153
	v_pk_add_f32 v[152:153], v[124:125], v[126:127]
	v_pk_mul_f32 v[106:107], v[124:125], v[106:107]
	v_mov_b32_e32 v123, v126
	v_pk_mul_f32 v[108:109], v[108:109], v[108:109]
	v_mov_b32_e32 v153, v107
	v_pk_fma_f32 v[108:109], v[122:123], v[122:123], v[108:109]
	v_pk_add_f32 v[112:113], v[112:113], v[154:155]
	v_pk_add_f32 v[106:107], v[120:121], v[152:153]
	v_pk_add_f32 v[108:109], v[108:109], v[108:109] op_sel_hi:[0,1]
	v_pk_add_f32 v[106:107], v[112:113], v[106:107]
	v_mov_b32_e32 v108, v1
	v_pk_add_f32 v[112:113], v[106:107], v[108:109]
	s_and_b64 vcc, exec, s[44:45]
	s_cbranch_vccnz .LBB0_619
	s_branch .LBB0_618

;     __device__ __forceinline__ void operator()(const f32x4 (&acc)[2][2][4][2], const pg8::Unit& u, int wr, int wc, int fr, int fq, LAS unsigned char* lds, int par) const {
;     ...
;                         const int pos = row & (SEQ - 1), i0 = (c & 63) >> 1;
;                         const f32x4 r0 = *(const f32x4*)(rope + ((size_t)pos * 32 + i0) * 2), r1 = *(const f32x4*)(rope + ((size_t)pos * 32 + i0 + 2) * 2);
;                         const float sc = (kind == 1) ? 0.125f : 1.0f;
;                         f32x4 o0, o1;
;                         o0[0] = (v0[0] * r0[0] - v0[1] * r0[1]) * sc; o0[1] = (v0[1] * r0[0] + v0[0] * r0[1]) * sc;
;                         o0[2] = (v0[2] * r0[2] - v0[3] * r0[3]) * sc; o0[3] = (v0[3] * r0[2] + v0[2] * r0[3]) * sc;
;                         o1[0] = (v1[0] * r1[0] - v1[1] * r1[1]) * sc; o1[1] = (v1[1] * r1[0] + v1[0] * r1[1]) * sc;
;                         o1[2] = (v1[2] * r1[2] - v1[3] * r1[3]) * sc; o1[3] = (v1[3] * r1[2] + v1[2] * r1[3]) * sc;
;                         v0 = o0; v1 = o1;
.LBB0_624:
	s_andn2_b64 vcc, exec, s[36:37]
	s_cbranch_vccnz .LBB0_626
	s_waitcnt vmcnt(1) lgkmcnt(0)
	v_mov_b32_e32 v106, v228
	v_mov_b32_e32 v107, v229
	v_mov_b32_e32 v108, v230
	v_mov_b32_e32 v109, v231
	v_mov_b32_e32 v116, v232
	v_mov_b32_e32 v117, v233
	v_mov_b32_e32 v118, v234
	v_mov_b32_e32 v119, v235
	v_or_b32_e32 v246, 32, v150
	v_lshlrev_b32_e32 v246, 5, v246
	v_and_b32_e32 v246, 0x1fde0, v246
	v_lshl_or_b32 v246, v246, 3, v168
	global_load_dwordx4 v[228:231], v246, s[12:13]
	global_load_dwordx4 v[232:235], v246, s[12:13] offset:16
	v_pk_mul_f32 v[120:121], v[102:103], v[106:107] op_sel:[1,1] op_sel_hi:[0,1]
	v_pk_fma_f32 v[122:123], v[102:103], v[106:107], v[120:121] neg_lo:[0,0,1] neg_hi:[0,0,1]
	v_pk_fma_f32 v[106:107], v[102:103], v[106:107], v[120:121] op_sel_hi:[1,0,1]
	v_mul_f32_e32 v120, v105, v109
	v_mov_b32_e32 v123, v107
	v_pk_mul_f32 v[106:107], v[148:149], v[122:123] op_sel_hi:[0,1]
	v_mul_f32_e32 v122, v105, v108
	v_pk_fma_f32 v[120:121], v[104:105], v[108:109], v[120:121] op_sel_hi:[1,1,0] neg_lo:[0,0,1] neg_hi:[0,0,1]
	v_pk_fma_f32 v[108:109], v[104:105], v[108:109], v[122:123] op_sel:[1,0,0] op_sel_hi:[0,1,0]
	v_mov_b32_e32 v121, v109
	v_pk_mul_f32 v[108:109], v[148:149], v[120:121] op_sel_hi:[0,1]
	v_pk_mul_f32 v[120:121], v[98:99], v[116:117] op_sel:[1,1] op_sel_hi:[0,1]
	v_pk_fma_f32 v[122:123], v[98:99], v[116:117], v[120:121] neg_lo:[0,0,1] neg_hi:[0,0,1]
	v_pk_fma_f32 v[116:117], v[98:99], v[116:117], v[120:121] op_sel_hi:[1,0,1]
	v_mul_f32_e32 v120, v101, v119
	v_mov_b32_e32 v123, v117
	v_pk_mul_f32 v[116:117], v[148:149], v[122:123] op_sel_hi:[0,1]
	v_mul_f32_e32 v122, v101, v118
	v_pk_fma_f32 v[120:121], v[100:101], v[118:119], v[120:121] op_sel_hi:[1,1,0] neg_lo:[0,0,1] neg_hi:[0,0,1]
	v_pk_fma_f32 v[118:119], v[100:101], v[118:119], v[122:123] op_sel:[1,0,0] op_sel_hi:[0,1,0]
	v_mov_b32_e32 v121, v119
	v_pk_mul_f32 v[118:119], v[148:149], v[120:121] op_sel_hi:[0,1]

; __device__ __forceinline__ float bf_lo(unsigned w) { return __uint_as_float(w << 16); }
; __device__ __forceinline__ float bf_hi(unsigned w) { return __uint_as_float(w & 0xffff0000u); }
; __device__ __forceinline__ float shflx(float v, int k, int lane) { return __int_as_float(__builtin_amdgcn_ds_bpermute((lane ^ k) << 2, __float_as_int(v))); }
; __device__ __forceinline__ u32x4 pack8(const f32x4 a, const f32x4 b) { u32x4 w; w.x = cvt_pk_bf16(a[0], a[1]); w.y = cvt_pk_bf16(a[2], a[3]); w.z = cvt_pk_bf16(b[0], b[1]); w.w = cvt_pk_bf16(b[2], b[3]); return w; }
;     __device__ __forceinline__ void operator()(const f32x4 (&acc)[2][2][4][2], const pg8::Unit& u, int wr, int wc, int fr, int fq, LAS unsigned char* lds, int par) const {
;     ...
;                     const u32x4 pw = pack8(v0, v1);
;                     *(u32x4*)(base + (size_t)row * ld + ct + c) = pw;
;                     if (kind == 0 && pn >= 4) {
;                         const float a0 = bf_lo(pw.x), a1 = bf_hi(pw.x), a2 = bf_lo(pw.y), a3 = bf_hi(pw.y), a4 = bf_lo(pw.z), a5 = bf_hi(pw.z), a6 = bf_lo(pw.w), a7 = bf_hi(pw.w);
;                         s1 += ((a0 + a1) + (a2 + a3)) + ((a4 + a5) + (a6 + a7));
;                         s2 += ((a0 * a0 + a1 * a1) + (a2 * a2 + a3 * a3)) + ((a4 * a4 + a5 * a5) + (a6 * a6 + a7 * a7));
;                     }
;                 }
;                 if (kind == 0 && pn >= 4) {
;                     s1 += shflx(s1, 16, fr + 16 * fq); s1 += shflx(s1, 32, fr + 16 * fq); s2 += shflx(s2, 16, fr + 16 * fq); s2 += shflx(s2, 32, fr + 16 * fq);
;                     if (fq == 0) { float* sp = statsv + ((size_t)row * 16 + (pn - 4) * 4 + wc) * 2; sp[0] = s1; sp[1] = s2; }
.LBB0_629:
	s_and_b64 vcc, exec, s[46:47]
	v_cvt_pk_bf16_f32 v98, v106, v107
	v_cvt_pk_bf16_f32 v99, v108, v109
	v_cvt_pk_bf16_f32 v100, v116, v117
	v_cvt_pk_bf16_f32 v101, v118, v119
	global_store_dwordx4 v[110:111], v[98:101], off offset:16
	s_cbranch_vccnz .LBB0_633
	v_lshlrev_b32_e32 v102, 16, v98
	v_and_b32_e32 v98, 0xffff0000, v98
	v_lshlrev_b32_e32 v104, 16, v99
	v_and_b32_e32 v106, 0xffff0000, v99
	v_lshlrev_b32_e32 v108, 16, v100
	v_and_b32_e32 v100, 0xffff0000, v100
	v_lshlrev_b32_e32 v110, 16, v101
	v_and_b32_e32 v116, 0xffff0000, v101
	v_mul_f32_e32 v103, v102, v102
	v_mul_f32_e32 v99, v98, v98
	v_mul_f32_e32 v105, v104, v104
	v_mul_f32_e32 v107, v106, v106
	v_mul_f32_e32 v109, v108, v108
	v_mul_f32_e32 v101, v100, v100
	v_mul_f32_e32 v111, v110, v110
	v_mul_f32_e32 v117, v116, v116
	v_pk_add_f32 v[98:99], v[102:103], v[98:99]
	v_pk_add_f32 v[102:103], v[104:105], v[106:107]
	v_pk_add_f32 v[100:101], v[108:109], v[100:101]
	v_pk_add_f32 v[98:99], v[98:99], v[102:103]
	v_pk_add_f32 v[102:103], v[110:111], v[116:117]
	s_nop 0
	v_pk_add_f32 v[100:101], v[100:101], v[102:103]
	s_nop 0
	v_pk_add_f32 v[98:99], v[98:99], v[100:101]
	s_nop 0
	v_pk_add_f32 v[98:99], v[112:113], v[98:99]
	ds_bpermute_b32 v100, v164, v98
	ds_bpermute_b32 v101, v164, v99
	s_waitcnt lgkmcnt(0)
	v_pk_add_f32 v[98:99], v[98:99], v[100:101]
	ds_bpermute_b32 v100, v165, v98
	ds_bpermute_b32 v101, v165, v99
	s_and_saveexec_b64 s[36:37], s[40:41]
	s_cbranch_execz .LBB0_632
	v_readlane_b32 s38, v252, 6
	v_lshlrev_b64 v[102:103], 7, v[114:115]
	v_readlane_b32 s39, v252, 7
	s_waitcnt lgkmcnt(0)
	v_pk_add_f32 v[98:99], v[98:99], v[100:101]
	v_lshl_add_u64 v[102:103], s[38:39], 0, v[102:103]
	v_lshl_add_u64 v[102:103], s[2:3], 3, v[102:103]
	global_store_dwordx2 v[102:103], v[98:99], off

;     __device__ __forceinline__ void operator()(const f32x4 (&acc)[2][2][4][2], const pg8::Unit& u, int wr, int wc, int fr, int fq, LAS unsigned char* lds, int par) const {
;     ...
;                         const int pos = row & (SEQ - 1), i0 = (c & 63) >> 1;
;                         const f32x4 r0 = *(const f32x4*)(rope + ((size_t)pos * 32 + i0) * 2), r1 = *(const f32x4*)(rope + ((size_t)pos * 32 + i0 + 2) * 2);
;                         const float sc = (kind == 1) ? 0.125f : 1.0f;
;                         f32x4 o0, o1;
;                         o0[0] = (v0[0] * r0[0] - v0[1] * r0[1]) * sc; o0[1] = (v0[1] * r0[0] + v0[0] * r0[1]) * sc;
;                         o0[2] = (v0[2] * r0[2] - v0[3] * r0[3]) * sc; o0[3] = (v0[3] * r0[2] + v0[2] * r0[3]) * sc;
;                         o1[0] = (v1[0] * r1[0] - v1[1] * r1[1]) * sc; o1[1] = (v1[1] * r1[0] + v1[0] * r1[1]) * sc;
;                         o1[2] = (v1[2] * r1[2] - v1[3] * r1[3]) * sc; o1[3] = (v1[3] * r1[2] + v1[2] * r1[3]) * sc;
;                         v0 = o0; v1 = o1;
.LBB0_642:
	s_andn2_b64 vcc, exec, s[36:37]
	s_cbranch_vccnz .LBB0_644
	s_waitcnt vmcnt(1) lgkmcnt(0)
	v_mov_b32_e32 v104, v228
	v_mov_b32_e32 v105, v229
	v_mov_b32_e32 v106, v230
	v_mov_b32_e32 v107, v231
	v_mov_b32_e32 v108, v232
	v_mov_b32_e32 v109, v233
	v_mov_b32_e32 v110, v234
	v_mov_b32_e32 v111, v235
	v_or_b32_e32 v246, v112, v178
	v_lshlrev_b32_e32 v246, 3, v246
	global_load_dwordx4 v[228:231], v246, s[12:13]
	global_load_dwordx4 v[232:235], v246, s[12:13] offset:16
	v_pk_mul_f32 v[114:115], v[94:95], v[104:105] op_sel:[1,1] op_sel_hi:[0,1]
	v_pk_fma_f32 v[116:117], v[94:95], v[104:105], v[114:115] neg_lo:[0,0,1] neg_hi:[0,0,1]
	v_pk_fma_f32 v[104:105], v[94:95], v[104:105], v[114:115] op_sel_hi:[1,0,1]
	v_mul_f32_e32 v114, v97, v107
	v_mov_b32_e32 v117, v105
	v_pk_mul_f32 v[104:105], v[148:149], v[116:117] op_sel_hi:[0,1]
	v_mul_f32_e32 v116, v97, v106
	v_pk_fma_f32 v[114:115], v[96:97], v[106:107], v[114:115] op_sel_hi:[1,1,0] neg_lo:[0,0,1] neg_hi:[0,0,1]
	v_pk_fma_f32 v[106:107], v[96:97], v[106:107], v[116:117] op_sel:[1,0,0] op_sel_hi:[0,1,0]
	v_mov_b32_e32 v115, v107
	v_pk_mul_f32 v[106:107], v[148:149], v[114:115] op_sel_hi:[0,1]
	v_pk_mul_f32 v[114:115], v[90:91], v[108:109] op_sel:[1,1] op_sel_hi:[0,1]
	v_pk_fma_f32 v[116:117], v[90:91], v[108:109], v[114:115] neg_lo:[0,0,1] neg_hi:[0,0,1]
	v_pk_fma_f32 v[108:109], v[90:91], v[108:109], v[114:115] op_sel_hi:[1,0,1]
	v_mul_f32_e32 v114, v93, v111
	v_mov_b32_e32 v117, v109
	v_pk_mul_f32 v[108:109], v[148:149], v[116:117] op_sel_hi:[0,1]
	v_mul_f32_e32 v116, v93, v110
	v_pk_fma_f32 v[114:115], v[92:93], v[110:111], v[114:115] op_sel_hi:[1,1,0] neg_lo:[0,0,1] neg_hi:[0,0,1]
	v_pk_fma_f32 v[110:111], v[92:93], v[110:111], v[116:117] op_sel:[1,0,0] op_sel_hi:[0,1,0]
	v_mov_b32_e32 v115, v111
	v_pk_mul_f32 v[110:111], v[148:149], v[114:115] op_sel_hi:[0,1]

; __device__ __forceinline__ float bf_lo(unsigned w) { return __uint_as_float(w << 16); }
; __device__ __forceinline__ float bf_hi(unsigned w) { return __uint_as_float(w & 0xffff0000u); }
; __device__ __forceinline__ u32x4 pack8(const f32x4 a, const f32x4 b) { u32x4 w; w.x = cvt_pk_bf16(a[0], a[1]); w.y = cvt_pk_bf16(a[2], a[3]); w.z = cvt_pk_bf16(b[0], b[1]); w.w = cvt_pk_bf16(b[2], b[3]); return w; }
;     __device__ __forceinline__ void operator()(const f32x4 (&acc)[2][2][4][2], const pg8::Unit& u, int wr, int wc, int fr, int fq, LAS unsigned char* lds, int par) const {
;     ...
;                     const u32x4 pw = pack8(v0, v1);
;                     *(u32x4*)(base + (size_t)row * ld + ct + c) = pw;
;                     if (kind == 0 && pn >= 4) {
;                         const float a0 = bf_lo(pw.x), a1 = bf_hi(pw.x), a2 = bf_lo(pw.y), a3 = bf_hi(pw.y), a4 = bf_lo(pw.z), a5 = bf_hi(pw.z), a6 = bf_lo(pw.w), a7 = bf_hi(pw.w);
;                         s1 += ((a0 + a1) + (a2 + a3)) + ((a4 + a5) + (a6 + a7));
;                         s2 += ((a0 * a0 + a1 * a1) + (a2 * a2 + a3 * a3)) + ((a4 * a4 + a5 * a5) + (a6 * a6 + a7 * a7));
;                     }
.LBB0_647:
	v_ashrrev_i32_e32 v99, 31, v98
	v_mul_lo_u32 v92, s29, v98
	v_mul_lo_u32 v93, s28, v99
	v_mad_u64_u32 v[90:91], s[36:37], s28, v98, 0
	v_add3_u32 v91, v91, v93, v92
	v_lshl_add_u64 v[94:95], v[90:91], 1, s[34:35]
	v_lshl_add_u64 v[94:95], v[94:95], 0, v[0:1]
	v_mov_b32_e32 v96, 0
	s_and_b64 vcc, exec, s[46:47]
	v_mov_b32_e32 v97, 0
	v_cvt_pk_bf16_f32 v90, v104, v105
	v_cvt_pk_bf16_f32 v91, v106, v107
	v_cvt_pk_bf16_f32 v92, v108, v109
	v_cvt_pk_bf16_f32 v93, v110, v111
	global_store_dwordx4 v[94:95], v[90:93], off
	s_cbranch_vccnz .LBB0_649
	v_and_b32_e32 v97, 16, v90
	v_and_b32_e32 v96, 0xffff0000, v90
	v_lshlrev_b32_e32 v107, 16, v91
	v_lshlrev_b32_e32 v106, 16, v92
	v_and_b32_e32 v104, 0xffff0000, v91
	v_mov_b32_e32 v105, v96
	v_pk_mov_b32 v[114:115], v[106:107], v[96:97] op_sel:[1,0]
	v_lshlrev_b32_e32 v90, 16, v90
	v_and_b32_e32 v108, 0xffff0000, v93
	v_mov_b32_e32 v109, v104
	v_and_b32_e32 v92, 0xffff0000, v92
	v_lshlrev_b32_e32 v110, 16, v93
	v_mov_b32_e32 v93, v107
	v_mov_b32_e32 v91, v104
	v_mov_b32_e32 v111, v104
	v_pk_add_f32 v[116:117], v[104:105], v[114:115]
	v_pk_mul_f32 v[104:105], v[104:105], v[114:115]
	v_pk_add_f32 v[96:97], v[90:91], v[96:97] op_sel_hi:[0,1]
	v_mov_b32_e32 v117, v105
	v_pk_add_f32 v[104:105], v[106:107], v[92:93]
	v_pk_mul_f32 v[114:115], v[106:107], v[106:107]
	v_mov_b32_e32 v93, v108
	v_mul_f32_e32 v97, v90, v90
	v_mov_b32_e32 v105, v115
	v_pk_add_f32 v[114:115], v[108:109], v[110:111]
	v_pk_mul_f32 v[90:91], v[108:109], v[90:91]
	v_mov_b32_e32 v107, v110
	v_pk_mul_f32 v[92:93], v[92:93], v[92:93]
	v_mov_b32_e32 v115, v91
	v_pk_fma_f32 v[92:93], v[106:107], v[106:107], v[92:93]
	v_pk_add_f32 v[96:97], v[96:97], v[116:117]
	v_pk_add_f32 v[90:91], v[104:105], v[114:115]
	v_pk_add_f32 v[92:93], v[92:93], v[92:93] op_sel_hi:[0,1]
	v_pk_add_f32 v[90:91], v[96:97], v[90:91]
	v_mov_b32_e32 v92, v1
	v_pk_add_f32 v[96:97], v[90:91], v[92:93]
	s_and_b64 vcc, exec, s[44:45]
	s_cbranch_vccnz .LBB0_651
	s_branch .LBB0_650

;     __device__ __forceinline__ void operator()(const f32x4 (&acc)[2][2][4][2], const pg8::Unit& u, int wr, int wc, int fr, int fq, LAS unsigned char* lds, int par) const {
;     ...
;                         const int pos = row & (SEQ - 1), i0 = (c & 63) >> 1;
;                         const f32x4 r0 = *(const f32x4*)(rope + ((size_t)pos * 32 + i0) * 2), r1 = *(const f32x4*)(rope + ((size_t)pos * 32 + i0 + 2) * 2);
;                         const float sc = (kind == 1) ? 0.125f : 1.0f;
;                         f32x4 o0, o1;
;                         o0[0] = (v0[0] * r0[0] - v0[1] * r0[1]) * sc; o0[1] = (v0[1] * r0[0] + v0[0] * r0[1]) * sc;
;                         o0[2] = (v0[2] * r0[2] - v0[3] * r0[3]) * sc; o0[3] = (v0[3] * r0[2] + v0[2] * r0[3]) * sc;
;                         o1[0] = (v1[0] * r1[0] - v1[1] * r1[1]) * sc; o1[1] = (v1[1] * r1[0] + v1[0] * r1[1]) * sc;
;                         o1[2] = (v1[2] * r1[2] - v1[3] * r1[3]) * sc; o1[3] = (v1[3] * r1[2] + v1[2] * r1[3]) * sc;
;                         v0 = o0; v1 = o1;
.LBB0_656:
	s_andn2_b64 vcc, exec, s[36:37]
	s_cbranch_vccnz .LBB0_658
	s_waitcnt vmcnt(1) lgkmcnt(0)
	v_mov_b32_e32 v90, v228
	v_mov_b32_e32 v91, v229
	v_mov_b32_e32 v92, v230
	v_mov_b32_e32 v93, v231
	v_mov_b32_e32 v100, v232
	v_mov_b32_e32 v101, v233
	v_mov_b32_e32 v102, v234
	v_mov_b32_e32 v103, v235
	v_or_b32_e32 v246, 48, v150
	v_lshlrev_b32_e32 v246, 5, v246
	v_and_b32_e32 v246, 0x1ffe0, v246
	v_lshl_or_b32 v246, v246, 3, v168
	global_load_dwordx4 v[228:231], v246, s[12:13]
	global_load_dwordx4 v[232:235], v246, s[12:13] offset:16
	v_pk_mul_f32 v[104:105], v[86:87], v[90:91] op_sel:[1,1] op_sel_hi:[0,1]
	v_pk_fma_f32 v[106:107], v[86:87], v[90:91], v[104:105] neg_lo:[0,0,1] neg_hi:[0,0,1]
	v_pk_fma_f32 v[90:91], v[86:87], v[90:91], v[104:105] op_sel_hi:[1,0,1]
	v_mul_f32_e32 v104, v89, v93
	v_mov_b32_e32 v107, v91
	v_pk_mul_f32 v[90:91], v[148:149], v[106:107] op_sel_hi:[0,1]
	v_mul_f32_e32 v106, v89, v92
	v_pk_fma_f32 v[104:105], v[88:89], v[92:93], v[104:105] op_sel_hi:[1,1,0] neg_lo:[0,0,1] neg_hi:[0,0,1]
	v_pk_fma_f32 v[92:93], v[88:89], v[92:93], v[106:107] op_sel:[1,0,0] op_sel_hi:[0,1,0]
	v_mov_b32_e32 v105, v93
	v_pk_mul_f32 v[92:93], v[148:149], v[104:105] op_sel_hi:[0,1]
	v_pk_mul_f32 v[104:105], v[82:83], v[100:101] op_sel:[1,1] op_sel_hi:[0,1]
	v_pk_fma_f32 v[106:107], v[82:83], v[100:101], v[104:105] neg_lo:[0,0,1] neg_hi:[0,0,1]
	v_pk_fma_f32 v[100:101], v[82:83], v[100:101], v[104:105] op_sel_hi:[1,0,1]
	v_mul_f32_e32 v104, v85, v103
	v_mov_b32_e32 v107, v101
	v_pk_mul_f32 v[100:101], v[148:149], v[106:107] op_sel_hi:[0,1]
	v_mul_f32_e32 v106, v85, v102
	v_pk_fma_f32 v[104:105], v[84:85], v[102:103], v[104:105] op_sel_hi:[1,1,0] neg_lo:[0,0,1] neg_hi:[0,0,1]
	v_pk_fma_f32 v[102:103], v[84:85], v[102:103], v[106:107] op_sel:[1,0,0] op_sel_hi:[0,1,0]
	v_mov_b32_e32 v105, v103
	v_pk_mul_f32 v[102:103], v[148:149], v[104:105] op_sel_hi:[0,1]

; __device__ __forceinline__ float bf_lo(unsigned w) { return __uint_as_float(w << 16); }
; __device__ __forceinline__ float bf_hi(unsigned w) { return __uint_as_float(w & 0xffff0000u); }
; __device__ __forceinline__ float shflx(float v, int k, int lane) { return __int_as_float(__builtin_amdgcn_ds_bpermute((lane ^ k) << 2, __float_as_int(v))); }
; __device__ __forceinline__ u32x4 pack8(const f32x4 a, const f32x4 b) { u32x4 w; w.x = cvt_pk_bf16(a[0], a[1]); w.y = cvt_pk_bf16(a[2], a[3]); w.z = cvt_pk_bf16(b[0], b[1]); w.w = cvt_pk_bf16(b[2], b[3]); return w; }
;     __device__ __forceinline__ void operator()(const f32x4 (&acc)[2][2][4][2], const pg8::Unit& u, int wr, int wc, int fr, int fq, LAS unsigned char* lds, int par) const {
;     ...
;                     const u32x4 pw = pack8(v0, v1);
;                     *(u32x4*)(base + (size_t)row * ld + ct + c) = pw;
;                     if (kind == 0 && pn >= 4) {
;                         const float a0 = bf_lo(pw.x), a1 = bf_hi(pw.x), a2 = bf_lo(pw.y), a3 = bf_hi(pw.y), a4 = bf_lo(pw.z), a5 = bf_hi(pw.z), a6 = bf_lo(pw.w), a7 = bf_hi(pw.w);
;                         s1 += ((a0 + a1) + (a2 + a3)) + ((a4 + a5) + (a6 + a7));
;                         s2 += ((a0 * a0 + a1 * a1) + (a2 * a2 + a3 * a3)) + ((a4 * a4 + a5 * a5) + (a6 * a6 + a7 * a7));
;                     }
;                 }
;                 if (kind == 0 && pn >= 4) {
;                     s1 += shflx(s1, 16, fr + 16 * fq); s1 += shflx(s1, 32, fr + 16 * fq); s2 += shflx(s2, 16, fr + 16 * fq); s2 += shflx(s2, 32, fr + 16 * fq);
;                     if (fq == 0) { float* sp = statsv + ((size_t)row * 16 + (pn - 4) * 4 + wc) * 2; sp[0] = s1; sp[1] = s2; }
.LBB0_661:
	s_and_b64 vcc, exec, s[46:47]
	v_cvt_pk_bf16_f32 v82, v90, v91
	v_cvt_pk_bf16_f32 v83, v92, v93
	v_cvt_pk_bf16_f32 v84, v100, v101
	v_cvt_pk_bf16_f32 v85, v102, v103
	global_store_dwordx4 v[94:95], v[82:85], off offset:16
	s_cbranch_vccnz .LBB0_665
	v_lshlrev_b32_e32 v86, 16, v82
	v_and_b32_e32 v82, 0xffff0000, v82
	v_lshlrev_b32_e32 v88, 16, v83
	v_and_b32_e32 v90, 0xffff0000, v83
	v_lshlrev_b32_e32 v92, 16, v84
	v_and_b32_e32 v84, 0xffff0000, v84
	v_lshlrev_b32_e32 v94, 16, v85
	v_and_b32_e32 v100, 0xffff0000, v85
	v_mul_f32_e32 v87, v86, v86
	v_mul_f32_e32 v83, v82, v82
	v_mul_f32_e32 v89, v88, v88
	v_mul_f32_e32 v91, v90, v90
	v_mul_f32_e32 v93, v92, v92
	v_mul_f32_e32 v85, v84, v84
	v_mul_f32_e32 v95, v94, v94
	v_mul_f32_e32 v101, v100, v100
	v_pk_add_f32 v[82:83], v[86:87], v[82:83]
	v_pk_add_f32 v[86:87], v[88:89], v[90:91]
	v_pk_add_f32 v[84:85], v[92:93], v[84:85]
	v_pk_add_f32 v[82:83], v[82:83], v[86:87]
	v_pk_add_f32 v[86:87], v[94:95], v[100:101]
	s_nop 0
	v_pk_add_f32 v[84:85], v[84:85], v[86:87]
	s_nop 0
	v_pk_add_f32 v[82:83], v[82:83], v[84:85]
	s_nop 0
	v_pk_add_f32 v[82:83], v[96:97], v[82:83]
	ds_bpermute_b32 v84, v164, v82
	ds_bpermute_b32 v85, v164, v83
	s_waitcnt lgkmcnt(0)
	v_pk_add_f32 v[82:83], v[82:83], v[84:85]
	ds_bpermute_b32 v84, v165, v82
	ds_bpermute_b32 v85, v165, v83
	s_and_saveexec_b64 s[36:37], s[40:41]
	s_cbranch_execz .LBB0_664
	v_readlane_b32 s38, v252, 6
	v_lshlrev_b64 v[86:87], 7, v[98:99]
	v_readlane_b32 s39, v252, 7
	s_waitcnt lgkmcnt(0)
	v_pk_add_f32 v[82:83], v[82:83], v[84:85]
	v_lshl_add_u64 v[86:87], s[38:39], 0, v[86:87]
	v_lshl_add_u64 v[86:87], s[2:3], 3, v[86:87]
	global_store_dwordx2 v[86:87], v[82:83], off

;     __device__ __forceinline__ void operator()(const f32x4 (&acc)[2][2][4][2], const pg8::Unit& u, int wr, int wc, int fr, int fq, LAS unsigned char* lds, int par) const {
;     ...
;                         const int pos = row & (SEQ - 1), i0 = (c & 63) >> 1;
;                         const f32x4 r0 = *(const f32x4*)(rope + ((size_t)pos * 32 + i0) * 2), r1 = *(const f32x4*)(rope + ((size_t)pos * 32 + i0 + 2) * 2);
;                         const float sc = (kind == 1) ? 0.125f : 1.0f;
;                         f32x4 o0, o1;
;                         o0[0] = (v0[0] * r0[0] - v0[1] * r0[1]) * sc; o0[1] = (v0[1] * r0[0] + v0[0] * r0[1]) * sc;
;                         o0[2] = (v0[2] * r0[2] - v0[3] * r0[3]) * sc; o0[3] = (v0[3] * r0[2] + v0[2] * r0[3]) * sc;
;                         o1[0] = (v1[0] * r1[0] - v1[1] * r1[1]) * sc; o1[1] = (v1[1] * r1[0] + v1[0] * r1[1]) * sc;
;                         o1[2] = (v1[2] * r1[2] - v1[3] * r1[3]) * sc; o1[3] = (v1[3] * r1[2] + v1[2] * r1[3]) * sc;
;                         v0 = o0; v1 = o1;
.LBB0_674:
	s_andn2_b64 vcc, exec, s[36:37]
	s_cbranch_vccnz .LBB0_676
	s_waitcnt vmcnt(1) lgkmcnt(0)
	v_mov_b32_e32 v88, v228
	v_mov_b32_e32 v89, v229
	v_mov_b32_e32 v90, v230
	v_mov_b32_e32 v91, v231
	v_mov_b32_e32 v92, v232
	v_mov_b32_e32 v93, v233
	v_mov_b32_e32 v94, v234
	v_mov_b32_e32 v95, v235
	v_or_b32_e32 v246, v96, v178
	v_lshlrev_b32_e32 v246, 3, v246
	global_load_dwordx4 v[228:231], v246, s[12:13]
	global_load_dwordx4 v[232:235], v246, s[12:13] offset:16
	v_pk_mul_f32 v[98:99], v[78:79], v[88:89] op_sel:[1,1] op_sel_hi:[0,1]
	v_pk_fma_f32 v[100:101], v[78:79], v[88:89], v[98:99] neg_lo:[0,0,1] neg_hi:[0,0,1]
	v_pk_fma_f32 v[88:89], v[78:79], v[88:89], v[98:99] op_sel_hi:[1,0,1]
	v_mul_f32_e32 v98, v81, v91
	v_mov_b32_e32 v101, v89
	v_pk_mul_f32 v[88:89], v[148:149], v[100:101] op_sel_hi:[0,1]
	v_mul_f32_e32 v100, v81, v90
	v_pk_fma_f32 v[98:99], v[80:81], v[90:91], v[98:99] op_sel_hi:[1,1,0] neg_lo:[0,0,1] neg_hi:[0,0,1]
	v_pk_fma_f32 v[90:91], v[80:81], v[90:91], v[100:101] op_sel:[1,0,0] op_sel_hi:[0,1,0]
	v_mov_b32_e32 v99, v91
	v_pk_mul_f32 v[90:91], v[148:149], v[98:99] op_sel_hi:[0,1]
	v_pk_mul_f32 v[98:99], v[74:75], v[92:93] op_sel:[1,1] op_sel_hi:[0,1]
	v_pk_fma_f32 v[100:101], v[74:75], v[92:93], v[98:99] neg_lo:[0,0,1] neg_hi:[0,0,1]
	v_pk_fma_f32 v[92:93], v[74:75], v[92:93], v[98:99] op_sel_hi:[1,0,1]
	v_mul_f32_e32 v98, v77, v95
	v_mov_b32_e32 v101, v93
	v_pk_mul_f32 v[92:93], v[148:149], v[100:101] op_sel_hi:[0,1]
	v_mul_f32_e32 v100, v77, v94
	v_pk_fma_f32 v[98:99], v[76:77], v[94:95], v[98:99] op_sel_hi:[1,1,0] neg_lo:[0,0,1] neg_hi:[0,0,1]
	v_pk_fma_f32 v[94:95], v[76:77], v[94:95], v[100:101] op_sel:[1,0,0] op_sel_hi:[0,1,0]
	v_mov_b32_e32 v99, v95
	v_pk_mul_f32 v[94:95], v[148:149], v[98:99] op_sel_hi:[0,1]

; __device__ __forceinline__ float bf_lo(unsigned w) { return __uint_as_float(w << 16); }
; __device__ __forceinline__ float bf_hi(unsigned w) { return __uint_as_float(w & 0xffff0000u); }
; __device__ __forceinline__ u32x4 pack8(const f32x4 a, const f32x4 b) { u32x4 w; w.x = cvt_pk_bf16(a[0], a[1]); w.y = cvt_pk_bf16(a[2], a[3]); w.z = cvt_pk_bf16(b[0], b[1]); w.w = cvt_pk_bf16(b[2], b[3]); return w; }
;     __device__ __forceinline__ void operator()(const f32x4 (&acc)[2][2][4][2], const pg8::Unit& u, int wr, int wc, int fr, int fq, LAS unsigned char* lds, int par) const {
;     ...
;                     const u32x4 pw = pack8(v0, v1);
;                     *(u32x4*)(base + (size_t)row * ld + ct + c) = pw;
;                     if (kind == 0 && pn >= 4) {
;                         const float a0 = bf_lo(pw.x), a1 = bf_hi(pw.x), a2 = bf_lo(pw.y), a3 = bf_hi(pw.y), a4 = bf_lo(pw.z), a5 = bf_hi(pw.z), a6 = bf_lo(pw.w), a7 = bf_hi(pw.w);
;                         s1 += ((a0 + a1) + (a2 + a3)) + ((a4 + a5) + (a6 + a7));
;                         s2 += ((a0 * a0 + a1 * a1) + (a2 * a2 + a3 * a3)) + ((a4 * a4 + a5 * a5) + (a6 * a6 + a7 * a7));
;                     }
.LBB0_679:
	v_ashrrev_i32_e32 v83, 31, v82
	v_mul_lo_u32 v76, s29, v82
	v_mul_lo_u32 v77, s28, v83
	v_mad_u64_u32 v[74:75], s[36:37], s28, v82, 0
	v_add3_u32 v75, v75, v77, v76
	v_lshl_add_u64 v[78:79], v[74:75], 1, s[34:35]
	v_lshl_add_u64 v[78:79], v[78:79], 0, v[0:1]
	v_mov_b32_e32 v80, 0
	s_and_b64 vcc, exec, s[46:47]
	v_mov_b32_e32 v81, 0
	v_cvt_pk_bf16_f32 v74, v88, v89
	v_cvt_pk_bf16_f32 v75, v90, v91
	v_cvt_pk_bf16_f32 v76, v92, v93
	v_cvt_pk_bf16_f32 v77, v94, v95
	global_store_dwordx4 v[78:79], v[74:77], off
	s_cbranch_vccnz .LBB0_681
	v_and_b32_e32 v81, 16, v74
	v_and_b32_e32 v80, 0xffff0000, v74
	v_lshlrev_b32_e32 v91, 16, v75
	v_lshlrev_b32_e32 v90, 16, v76
	v_and_b32_e32 v88, 0xffff0000, v75
	v_mov_b32_e32 v89, v80
	v_pk_mov_b32 v[98:99], v[90:91], v[80:81] op_sel:[1,0]
	v_lshlrev_b32_e32 v74, 16, v74
	v_and_b32_e32 v92, 0xffff0000, v77
	v_mov_b32_e32 v93, v88
	v_and_b32_e32 v76, 0xffff0000, v76
	v_lshlrev_b32_e32 v94, 16, v77
	v_mov_b32_e32 v77, v91
	v_mov_b32_e32 v75, v88
	v_mov_b32_e32 v95, v88
	v_pk_add_f32 v[100:101], v[88:89], v[98:99]
	v_pk_mul_f32 v[88:89], v[88:89], v[98:99]
	v_pk_add_f32 v[80:81], v[74:75], v[80:81] op_sel_hi:[0,1]
	v_mov_b32_e32 v101, v89
	v_pk_add_f32 v[88:89], v[90:91], v[76:77]
	v_pk_mul_f32 v[98:99], v[90:91], v[90:91]
	v_mov_b32_e32 v77, v92
	v_mul_f32_e32 v81, v74, v74
	v_mov_b32_e32 v89, v99
	v_pk_add_f32 v[98:99], v[92:93], v[94:95]
	v_pk_mul_f32 v[74:75], v[92:93], v[74:75]
	v_mov_b32_e32 v91, v94
	v_pk_mul_f32 v[76:77], v[76:77], v[76:77]
	v_mov_b32_e32 v99, v75
	v_pk_fma_f32 v[76:77], v[90:91], v[90:91], v[76:77]
	v_pk_add_f32 v[80:81], v[80:81], v[100:101]
	v_pk_add_f32 v[74:75], v[88:89], v[98:99]
	v_pk_add_f32 v[76:77], v[76:77], v[76:77] op_sel_hi:[0,1]
	v_pk_add_f32 v[74:75], v[80:81], v[74:75]
	v_mov_b32_e32 v76, v1
	v_pk_add_f32 v[80:81], v[74:75], v[76:77]
	s_and_b64 vcc, exec, s[44:45]
	s_cbranch_vccnz .LBB0_683
	s_branch .LBB0_682

;     __device__ __forceinline__ void operator()(const f32x4 (&acc)[2][2][4][2], const pg8::Unit& u, int wr, int wc, int fr, int fq, LAS unsigned char* lds, int par) const {
;     ...
;                         const int pos = row & (SEQ - 1), i0 = (c & 63) >> 1;
;                         const f32x4 r0 = *(const f32x4*)(rope + ((size_t)pos * 32 + i0) * 2), r1 = *(const f32x4*)(rope + ((size_t)pos * 32 + i0 + 2) * 2);
;                         const float sc = (kind == 1) ? 0.125f : 1.0f;
;                         f32x4 o0, o1;
;                         o0[0] = (v0[0] * r0[0] - v0[1] * r0[1]) * sc; o0[1] = (v0[1] * r0[0] + v0[0] * r0[1]) * sc;
;                         o0[2] = (v0[2] * r0[2] - v0[3] * r0[3]) * sc; o0[3] = (v0[3] * r0[2] + v0[2] * r0[3]) * sc;
;                         o1[0] = (v1[0] * r1[0] - v1[1] * r1[1]) * sc; o1[1] = (v1[1] * r1[0] + v1[0] * r1[1]) * sc;
;                         o1[2] = (v1[2] * r1[2] - v1[3] * r1[3]) * sc; o1[3] = (v1[3] * r1[2] + v1[2] * r1[3]) * sc;
;                         v0 = o0; v1 = o1;
.LBB0_688:
	s_andn2_b64 vcc, exec, s[36:37]
	s_cbranch_vccnz .LBB0_690
	s_waitcnt vmcnt(1) lgkmcnt(0)
	v_mov_b32_e32 v74, v228
	v_mov_b32_e32 v75, v229
	v_mov_b32_e32 v76, v230
	v_mov_b32_e32 v77, v231
	v_mov_b32_e32 v84, v232
	v_mov_b32_e32 v85, v233
	v_mov_b32_e32 v86, v234
	v_mov_b32_e32 v87, v235
	v_add_u32_e32 v246, 0x80, v150
	v_lshlrev_b32_e32 v246, 5, v246
	v_and_b32_e32 v246, 0x1f9e0, v246
	v_lshl_or_b32 v246, v246, 3, v168
	global_load_dwordx4 v[228:231], v246, s[12:13]
	global_load_dwordx4 v[232:235], v246, s[12:13] offset:16
	v_pk_mul_f32 v[88:89], v[70:71], v[74:75] op_sel:[1,1] op_sel_hi:[0,1]
	v_pk_fma_f32 v[90:91], v[70:71], v[74:75], v[88:89] neg_lo:[0,0,1] neg_hi:[0,0,1]
	v_pk_fma_f32 v[74:75], v[70:71], v[74:75], v[88:89] op_sel_hi:[1,0,1]
	v_mul_f32_e32 v88, v73, v77
	v_mov_b32_e32 v91, v75
	v_pk_mul_f32 v[74:75], v[148:149], v[90:91] op_sel_hi:[0,1]
	v_mul_f32_e32 v90, v73, v76
	v_pk_fma_f32 v[88:89], v[72:73], v[76:77], v[88:89] op_sel_hi:[1,1,0] neg_lo:[0,0,1] neg_hi:[0,0,1]
	v_pk_fma_f32 v[76:77], v[72:73], v[76:77], v[90:91] op_sel:[1,0,0] op_sel_hi:[0,1,0]
	v_mov_b32_e32 v89, v77
	v_pk_mul_f32 v[76:77], v[148:149], v[88:89] op_sel_hi:[0,1]
	v_pk_mul_f32 v[88:89], v[66:67], v[84:85] op_sel:[1,1] op_sel_hi:[0,1]
	v_pk_fma_f32 v[90:91], v[66:67], v[84:85], v[88:89] neg_lo:[0,0,1] neg_hi:[0,0,1]
	v_pk_fma_f32 v[84:85], v[66:67], v[84:85], v[88:89] op_sel_hi:[1,0,1]
	v_mul_f32_e32 v88, v69, v87
	v_mov_b32_e32 v91, v85
	v_pk_mul_f32 v[84:85], v[148:149], v[90:91] op_sel_hi:[0,1]
	v_mul_f32_e32 v90, v69, v86
	v_pk_fma_f32 v[88:89], v[68:69], v[86:87], v[88:89] op_sel_hi:[1,1,0] neg_lo:[0,0,1] neg_hi:[0,0,1]
	v_pk_fma_f32 v[86:87], v[68:69], v[86:87], v[90:91] op_sel:[1,0,0] op_sel_hi:[0,1,0]
	v_mov_b32_e32 v89, v87
	v_pk_mul_f32 v[86:87], v[148:149], v[88:89] op_sel_hi:[0,1]

; __device__ __forceinline__ float bf_lo(unsigned w) { return __uint_as_float(w << 16); }
; __device__ __forceinline__ float bf_hi(unsigned w) { return __uint_as_float(w & 0xffff0000u); }
; __device__ __forceinline__ float shflx(float v, int k, int lane) { return __int_as_float(__builtin_amdgcn_ds_bpermute((lane ^ k) << 2, __float_as_int(v))); }
; __device__ __forceinline__ u32x4 pack8(const f32x4 a, const f32x4 b) { u32x4 w; w.x = cvt_pk_bf16(a[0], a[1]); w.y = cvt_pk_bf16(a[2], a[3]); w.z = cvt_pk_bf16(b[0], b[1]); w.w = cvt_pk_bf16(b[2], b[3]); return w; }
;     __device__ __forceinline__ void operator()(const f32x4 (&acc)[2][2][4][2], const pg8::Unit& u, int wr, int wc, int fr, int fq, LAS unsigned char* lds, int par) const {
;     ...
;                     const u32x4 pw = pack8(v0, v1);
;                     *(u32x4*)(base + (size_t)row * ld + ct + c) = pw;
;                     if (kind == 0 && pn >= 4) {
;                         const float a0 = bf_lo(pw.x), a1 = bf_hi(pw.x), a2 = bf_lo(pw.y), a3 = bf_hi(pw.y), a4 = bf_lo(pw.z), a5 = bf_hi(pw.z), a6 = bf_lo(pw.w), a7 = bf_hi(pw.w);
;                         s1 += ((a0 + a1) + (a2 + a3)) + ((a4 + a5) + (a6 + a7));
;                         s2 += ((a0 * a0 + a1 * a1) + (a2 * a2 + a3 * a3)) + ((a4 * a4 + a5 * a5) + (a6 * a6 + a7 * a7));
;                     }
;                 }
;                 if (kind == 0 && pn >= 4) {
;                     s1 += shflx(s1, 16, fr + 16 * fq); s1 += shflx(s1, 32, fr + 16 * fq); s2 += shflx(s2, 16, fr + 16 * fq); s2 += shflx(s2, 32, fr + 16 * fq);
;                     if (fq == 0) { float* sp = statsv + ((size_t)row * 16 + (pn - 4) * 4 + wc) * 2; sp[0] = s1; sp[1] = s2; }
.LBB0_693:
	s_and_b64 vcc, exec, s[46:47]
	v_cvt_pk_bf16_f32 v66, v74, v75
	v_cvt_pk_bf16_f32 v67, v76, v77
	v_cvt_pk_bf16_f32 v68, v84, v85
	v_cvt_pk_bf16_f32 v69, v86, v87
	global_store_dwordx4 v[78:79], v[66:69], off offset:16
	s_cbranch_vccnz .LBB0_697
	v_lshlrev_b32_e32 v70, 16, v66
	v_and_b32_e32 v66, 0xffff0000, v66
	v_lshlrev_b32_e32 v72, 16, v67
	v_and_b32_e32 v74, 0xffff0000, v67
	v_lshlrev_b32_e32 v76, 16, v68
	v_and_b32_e32 v68, 0xffff0000, v68
	v_lshlrev_b32_e32 v78, 16, v69
	v_and_b32_e32 v84, 0xffff0000, v69
	v_mul_f32_e32 v71, v70, v70
	v_mul_f32_e32 v67, v66, v66
	v_mul_f32_e32 v73, v72, v72
	v_mul_f32_e32 v75, v74, v74
	v_mul_f32_e32 v77, v76, v76
	v_mul_f32_e32 v69, v68, v68
	v_mul_f32_e32 v79, v78, v78
	v_mul_f32_e32 v85, v84, v84
	v_pk_add_f32 v[66:67], v[70:71], v[66:67]
	v_pk_add_f32 v[70:71], v[72:73], v[74:75]
	v_pk_add_f32 v[68:69], v[76:77], v[68:69]
	v_pk_add_f32 v[66:67], v[66:67], v[70:71]
	v_pk_add_f32 v[70:71], v[78:79], v[84:85]
	s_nop 0
	v_pk_add_f32 v[68:69], v[68:69], v[70:71]
	s_nop 0
	v_pk_add_f32 v[66:67], v[66:67], v[68:69]
	s_nop 0
	v_pk_add_f32 v[66:67], v[80:81], v[66:67]
	ds_bpermute_b32 v68, v164, v66
	ds_bpermute_b32 v69, v164, v67
	s_waitcnt lgkmcnt(0)
	v_pk_add_f32 v[66:67], v[66:67], v[68:69]
	ds_bpermute_b32 v68, v165, v66
	ds_bpermute_b32 v69, v165, v67
	s_and_saveexec_b64 s[36:37], s[40:41]
	s_cbranch_execz .LBB0_696
	v_readlane_b32 s38, v252, 6
	v_lshlrev_b64 v[70:71], 7, v[82:83]
	v_readlane_b32 s39, v252, 7
	s_waitcnt lgkmcnt(0)
	v_pk_add_f32 v[66:67], v[66:67], v[68:69]
	v_lshl_add_u64 v[70:71], s[38:39], 0, v[70:71]
	v_lshl_add_u64 v[70:71], s[2:3], 3, v[70:71]
	global_store_dwordx2 v[70:71], v[66:67], off

;     __device__ __forceinline__ void operator()(const f32x4 (&acc)[2][2][4][2], const pg8::Unit& u, int wr, int wc, int fr, int fq, LAS unsigned char* lds, int par) const {
;     ...
;                         const int pos = row & (SEQ - 1), i0 = (c & 63) >> 1;
;                         const f32x4 r0 = *(const f32x4*)(rope + ((size_t)pos * 32 + i0) * 2), r1 = *(const f32x4*)(rope + ((size_t)pos * 32 + i0 + 2) * 2);
;                         const float sc = (kind == 1) ? 0.125f : 1.0f;
;                         f32x4 o0, o1;
;                         o0[0] = (v0[0] * r0[0] - v0[1] * r0[1]) * sc; o0[1] = (v0[1] * r0[0] + v0[0] * r0[1]) * sc;
;                         o0[2] = (v0[2] * r0[2] - v0[3] * r0[3]) * sc; o0[3] = (v0[3] * r0[2] + v0[2] * r0[3]) * sc;
;                         o1[0] = (v1[0] * r1[0] - v1[1] * r1[1]) * sc; o1[1] = (v1[1] * r1[0] + v1[0] * r1[1]) * sc;
;                         o1[2] = (v1[2] * r1[2] - v1[3] * r1[3]) * sc; o1[3] = (v1[3] * r1[2] + v1[2] * r1[3]) * sc;
;                         v0 = o0; v1 = o1;
.LBB0_706:
	s_andn2_b64 vcc, exec, s[36:37]
	s_cbranch_vccnz .LBB0_708
	s_waitcnt vmcnt(1) lgkmcnt(0)
	v_mov_b32_e32 v72, v228
	v_mov_b32_e32 v73, v229
	v_mov_b32_e32 v74, v230
	v_mov_b32_e32 v75, v231
	v_mov_b32_e32 v76, v232
	v_mov_b32_e32 v77, v233
	v_mov_b32_e32 v78, v234
	v_mov_b32_e32 v79, v235
	v_or_b32_e32 v246, v80, v178
	v_lshlrev_b32_e32 v246, 3, v246
	global_load_dwordx4 v[228:231], v246, s[12:13]
	global_load_dwordx4 v[232:235], v246, s[12:13] offset:16
	v_pk_mul_f32 v[82:83], v[62:63], v[72:73] op_sel:[1,1] op_sel_hi:[0,1]
	v_pk_fma_f32 v[84:85], v[62:63], v[72:73], v[82:83] neg_lo:[0,0,1] neg_hi:[0,0,1]
	v_pk_fma_f32 v[72:73], v[62:63], v[72:73], v[82:83] op_sel_hi:[1,0,1]
	v_mul_f32_e32 v82, v65, v75
	v_mov_b32_e32 v85, v73
	v_pk_mul_f32 v[72:73], v[148:149], v[84:85] op_sel_hi:[0,1]
	v_mul_f32_e32 v84, v65, v74
	v_pk_fma_f32 v[82:83], v[64:65], v[74:75], v[82:83] op_sel_hi:[1,1,0] neg_lo:[0,0,1] neg_hi:[0,0,1]
	v_pk_fma_f32 v[74:75], v[64:65], v[74:75], v[84:85] op_sel:[1,0,0] op_sel_hi:[0,1,0]
	v_mov_b32_e32 v83, v75
	v_pk_mul_f32 v[74:75], v[148:149], v[82:83] op_sel_hi:[0,1]
	v_pk_mul_f32 v[82:83], v[58:59], v[76:77] op_sel:[1,1] op_sel_hi:[0,1]
	v_pk_fma_f32 v[84:85], v[58:59], v[76:77], v[82:83] neg_lo:[0,0,1] neg_hi:[0,0,1]
	v_pk_fma_f32 v[76:77], v[58:59], v[76:77], v[82:83] op_sel_hi:[1,0,1]
	v_mul_f32_e32 v82, v61, v79
	v_mov_b32_e32 v85, v77
	v_pk_mul_f32 v[76:77], v[148:149], v[84:85] op_sel_hi:[0,1]
	v_mul_f32_e32 v84, v61, v78
	v_pk_fma_f32 v[82:83], v[60:61], v[78:79], v[82:83] op_sel_hi:[1,1,0] neg_lo:[0,0,1] neg_hi:[0,0,1]
	v_pk_fma_f32 v[78:79], v[60:61], v[78:79], v[84:85] op_sel:[1,0,0] op_sel_hi:[0,1,0]
	v_mov_b32_e32 v83, v79
	v_pk_mul_f32 v[78:79], v[148:149], v[82:83] op_sel_hi:[0,1]

; __device__ __forceinline__ float bf_lo(unsigned w) { return __uint_as_float(w << 16); }
; __device__ __forceinline__ float bf_hi(unsigned w) { return __uint_as_float(w & 0xffff0000u); }
; __device__ __forceinline__ u32x4 pack8(const f32x4 a, const f32x4 b) { u32x4 w; w.x = cvt_pk_bf16(a[0], a[1]); w.y = cvt_pk_bf16(a[2], a[3]); w.z = cvt_pk_bf16(b[0], b[1]); w.w = cvt_pk_bf16(b[2], b[3]); return w; }
;     __device__ __forceinline__ void operator()(const f32x4 (&acc)[2][2][4][2], const pg8::Unit& u, int wr, int wc, int fr, int fq, LAS unsigned char* lds, int par) const {
;     ...
;                     const u32x4 pw = pack8(v0, v1);
;                     *(u32x4*)(base + (size_t)row * ld + ct + c) = pw;
;                     if (kind == 0 && pn >= 4) {
;                         const float a0 = bf_lo(pw.x), a1 = bf_hi(pw.x), a2 = bf_lo(pw.y), a3 = bf_hi(pw.y), a4 = bf_lo(pw.z), a5 = bf_hi(pw.z), a6 = bf_lo(pw.w), a7 = bf_hi(pw.w);
;                         s1 += ((a0 + a1) + (a2 + a3)) + ((a4 + a5) + (a6 + a7));
;                         s2 += ((a0 * a0 + a1 * a1) + (a2 * a2 + a3 * a3)) + ((a4 * a4 + a5 * a5) + (a6 * a6 + a7 * a7));
;                     }
.LBB0_711:
	v_ashrrev_i32_e32 v67, 31, v66
	v_mul_lo_u32 v60, s29, v66
	v_mul_lo_u32 v61, s28, v67
	v_mad_u64_u32 v[58:59], s[36:37], s28, v66, 0
	v_add3_u32 v59, v59, v61, v60
	v_lshl_add_u64 v[62:63], v[58:59], 1, s[34:35]
	v_lshl_add_u64 v[62:63], v[62:63], 0, v[0:1]
	v_mov_b32_e32 v64, 0
	s_and_b64 vcc, exec, s[46:47]
	v_mov_b32_e32 v65, 0
	v_cvt_pk_bf16_f32 v58, v72, v73
	v_cvt_pk_bf16_f32 v59, v74, v75
	v_cvt_pk_bf16_f32 v60, v76, v77
	v_cvt_pk_bf16_f32 v61, v78, v79
	global_store_dwordx4 v[62:63], v[58:61], off
	s_cbranch_vccnz .LBB0_713
	v_and_b32_e32 v65, 16, v58
	v_and_b32_e32 v64, 0xffff0000, v58
	v_lshlrev_b32_e32 v75, 16, v59
	v_lshlrev_b32_e32 v74, 16, v60
	v_and_b32_e32 v72, 0xffff0000, v59
	v_mov_b32_e32 v73, v64
	v_pk_mov_b32 v[82:83], v[74:75], v[64:65] op_sel:[1,0]
	v_lshlrev_b32_e32 v58, 16, v58
	v_and_b32_e32 v76, 0xffff0000, v61
	v_mov_b32_e32 v77, v72
	v_and_b32_e32 v60, 0xffff0000, v60
	v_lshlrev_b32_e32 v78, 16, v61
	v_mov_b32_e32 v61, v75
	v_mov_b32_e32 v59, v72
	v_mov_b32_e32 v79, v72
	v_pk_add_f32 v[84:85], v[72:73], v[82:83]
	v_pk_mul_f32 v[72:73], v[72:73], v[82:83]
	v_pk_add_f32 v[64:65], v[58:59], v[64:65] op_sel_hi:[0,1]
	v_mov_b32_e32 v85, v73
	v_pk_add_f32 v[72:73], v[74:75], v[60:61]
	v_pk_mul_f32 v[82:83], v[74:75], v[74:75]
	v_mov_b32_e32 v61, v76
	v_mul_f32_e32 v65, v58, v58
	v_mov_b32_e32 v73, v83
	v_pk_add_f32 v[82:83], v[76:77], v[78:79]
	v_pk_mul_f32 v[58:59], v[76:77], v[58:59]
	v_mov_b32_e32 v75, v78
	v_pk_mul_f32 v[60:61], v[60:61], v[60:61]
	v_mov_b32_e32 v83, v59
	v_pk_fma_f32 v[60:61], v[74:75], v[74:75], v[60:61]
	v_pk_add_f32 v[64:65], v[64:65], v[84:85]
	v_pk_add_f32 v[58:59], v[72:73], v[82:83]
	v_pk_add_f32 v[60:61], v[60:61], v[60:61] op_sel_hi:[0,1]
	v_pk_add_f32 v[58:59], v[64:65], v[58:59]
	v_mov_b32_e32 v60, v1
	v_pk_add_f32 v[64:65], v[58:59], v[60:61]
	s_and_b64 vcc, exec, s[44:45]
	s_cbranch_vccnz .LBB0_715
	s_branch .LBB0_714

;     __device__ __forceinline__ void operator()(const f32x4 (&acc)[2][2][4][2], const pg8::Unit& u, int wr, int wc, int fr, int fq, LAS unsigned char* lds, int par) const {
;     ...
;                         const int pos = row & (SEQ - 1), i0 = (c & 63) >> 1;
;                         const f32x4 r0 = *(const f32x4*)(rope + ((size_t)pos * 32 + i0) * 2), r1 = *(const f32x4*)(rope + ((size_t)pos * 32 + i0 + 2) * 2);
;                         const float sc = (kind == 1) ? 0.125f : 1.0f;
;                         f32x4 o0, o1;
;                         o0[0] = (v0[0] * r0[0] - v0[1] * r0[1]) * sc; o0[1] = (v0[1] * r0[0] + v0[0] * r0[1]) * sc;
;                         o0[2] = (v0[2] * r0[2] - v0[3] * r0[3]) * sc; o0[3] = (v0[3] * r0[2] + v0[2] * r0[3]) * sc;
;                         o1[0] = (v1[0] * r1[0] - v1[1] * r1[1]) * sc; o1[1] = (v1[1] * r1[0] + v1[0] * r1[1]) * sc;
;                         o1[2] = (v1[2] * r1[2] - v1[3] * r1[3]) * sc; o1[3] = (v1[3] * r1[2] + v1[2] * r1[3]) * sc;
;                         v0 = o0; v1 = o1;
.LBB0_720:
	s_andn2_b64 vcc, exec, s[36:37]
	s_cbranch_vccnz .LBB0_722
	s_waitcnt vmcnt(1) lgkmcnt(0)
	v_mov_b32_e32 v58, v228
	v_mov_b32_e32 v59, v229
	v_mov_b32_e32 v60, v230
	v_mov_b32_e32 v61, v231
	v_mov_b32_e32 v68, v232
	v_mov_b32_e32 v69, v233
	v_mov_b32_e32 v70, v234
	v_mov_b32_e32 v71, v235
	v_add_u32_e32 v246, 0x90, v150
	v_lshlrev_b32_e32 v246, 5, v246
	v_and_b32_e32 v246, 0x1fbe0, v246
	v_lshl_or_b32 v246, v246, 3, v168
	global_load_dwordx4 v[228:231], v246, s[12:13]
	global_load_dwordx4 v[232:235], v246, s[12:13] offset:16
	v_pk_mul_f32 v[72:73], v[54:55], v[58:59] op_sel:[1,1] op_sel_hi:[0,1]
	v_pk_fma_f32 v[74:75], v[54:55], v[58:59], v[72:73] neg_lo:[0,0,1] neg_hi:[0,0,1]
	v_pk_fma_f32 v[58:59], v[54:55], v[58:59], v[72:73] op_sel_hi:[1,0,1]
	v_mul_f32_e32 v72, v57, v61
	v_mov_b32_e32 v75, v59
	v_pk_mul_f32 v[58:59], v[148:149], v[74:75] op_sel_hi:[0,1]
	v_mul_f32_e32 v74, v57, v60
	v_pk_fma_f32 v[72:73], v[56:57], v[60:61], v[72:73] op_sel_hi:[1,1,0] neg_lo:[0,0,1] neg_hi:[0,0,1]
	v_pk_fma_f32 v[60:61], v[56:57], v[60:61], v[74:75] op_sel:[1,0,0] op_sel_hi:[0,1,0]
	v_mov_b32_e32 v73, v61
	v_pk_mul_f32 v[60:61], v[148:149], v[72:73] op_sel_hi:[0,1]
	v_pk_mul_f32 v[72:73], v[50:51], v[68:69] op_sel:[1,1] op_sel_hi:[0,1]
	v_pk_fma_f32 v[74:75], v[50:51], v[68:69], v[72:73] neg_lo:[0,0,1] neg_hi:[0,0,1]
	v_pk_fma_f32 v[68:69], v[50:51], v[68:69], v[72:73] op_sel_hi:[1,0,1]
	v_mul_f32_e32 v72, v53, v71
	v_mov_b32_e32 v75, v69
	v_pk_mul_f32 v[68:69], v[148:149], v[74:75] op_sel_hi:[0,1]
	v_mul_f32_e32 v74, v53, v70
	v_pk_fma_f32 v[72:73], v[52:53], v[70:71], v[72:73] op_sel_hi:[1,1,0] neg_lo:[0,0,1] neg_hi:[0,0,1]
	v_pk_fma_f32 v[70:71], v[52:53], v[70:71], v[74:75] op_sel:[1,0,0] op_sel_hi:[0,1,0]
	v_mov_b32_e32 v73, v71
	v_pk_mul_f32 v[70:71], v[148:149], v[72:73] op_sel_hi:[0,1]

; __device__ __forceinline__ float bf_lo(unsigned w) { return __uint_as_float(w << 16); }
; __device__ __forceinline__ float bf_hi(unsigned w) { return __uint_as_float(w & 0xffff0000u); }
; __device__ __forceinline__ float shflx(float v, int k, int lane) { return __int_as_float(__builtin_amdgcn_ds_bpermute((lane ^ k) << 2, __float_as_int(v))); }
; __device__ __forceinline__ u32x4 pack8(const f32x4 a, const f32x4 b) { u32x4 w; w.x = cvt_pk_bf16(a[0], a[1]); w.y = cvt_pk_bf16(a[2], a[3]); w.z = cvt_pk_bf16(b[0], b[1]); w.w = cvt_pk_bf16(b[2], b[3]); return w; }
;     __device__ __forceinline__ void operator()(const f32x4 (&acc)[2][2][4][2], const pg8::Unit& u, int wr, int wc, int fr, int fq, LAS unsigned char* lds, int par) const {
;     ...
;                     const u32x4 pw = pack8(v0, v1);
;                     *(u32x4*)(base + (size_t)row * ld + ct + c) = pw;
;                     if (kind == 0 && pn >= 4) {
;                         const float a0 = bf_lo(pw.x), a1 = bf_hi(pw.x), a2 = bf_lo(pw.y), a3 = bf_hi(pw.y), a4 = bf_lo(pw.z), a5 = bf_hi(pw.z), a6 = bf_lo(pw.w), a7 = bf_hi(pw.w);
;                         s1 += ((a0 + a1) + (a2 + a3)) + ((a4 + a5) + (a6 + a7));
;                         s2 += ((a0 * a0 + a1 * a1) + (a2 * a2 + a3 * a3)) + ((a4 * a4 + a5 * a5) + (a6 * a6 + a7 * a7));
;                     }
;                 }
;                 if (kind == 0 && pn >= 4) {
;                     s1 += shflx(s1, 16, fr + 16 * fq); s1 += shflx(s1, 32, fr + 16 * fq); s2 += shflx(s2, 16, fr + 16 * fq); s2 += shflx(s2, 32, fr + 16 * fq);
;                     if (fq == 0) { float* sp = statsv + ((size_t)row * 16 + (pn - 4) * 4 + wc) * 2; sp[0] = s1; sp[1] = s2; }
.LBB0_725:
	s_and_b64 vcc, exec, s[46:47]
	v_cvt_pk_bf16_f32 v50, v58, v59
	v_cvt_pk_bf16_f32 v51, v60, v61
	v_cvt_pk_bf16_f32 v52, v68, v69
	v_cvt_pk_bf16_f32 v53, v70, v71
	global_store_dwordx4 v[62:63], v[50:53], off offset:16
	s_cbranch_vccnz .LBB0_729
	v_lshlrev_b32_e32 v54, 16, v50
	v_and_b32_e32 v50, 0xffff0000, v50
	v_lshlrev_b32_e32 v56, 16, v51
	v_and_b32_e32 v58, 0xffff0000, v51
	v_lshlrev_b32_e32 v60, 16, v52
	v_and_b32_e32 v52, 0xffff0000, v52
	v_lshlrev_b32_e32 v62, 16, v53
	v_and_b32_e32 v68, 0xffff0000, v53
	v_mul_f32_e32 v55, v54, v54
	v_mul_f32_e32 v51, v50, v50
	v_mul_f32_e32 v57, v56, v56
	v_mul_f32_e32 v59, v58, v58
	v_mul_f32_e32 v61, v60, v60
	v_mul_f32_e32 v53, v52, v52
	v_mul_f32_e32 v63, v62, v62
	v_mul_f32_e32 v69, v68, v68
	v_pk_add_f32 v[50:51], v[54:55], v[50:51]
	v_pk_add_f32 v[54:55], v[56:57], v[58:59]
	v_pk_add_f32 v[52:53], v[60:61], v[52:53]
	v_pk_add_f32 v[50:51], v[50:51], v[54:55]
	v_pk_add_f32 v[54:55], v[62:63], v[68:69]
	s_nop 0
	v_pk_add_f32 v[52:53], v[52:53], v[54:55]
	s_nop 0
	v_pk_add_f32 v[50:51], v[50:51], v[52:53]
	s_nop 0
	v_pk_add_f32 v[50:51], v[64:65], v[50:51]
	ds_bpermute_b32 v52, v164, v50
	ds_bpermute_b32 v53, v164, v51
	s_waitcnt lgkmcnt(0)
	v_pk_add_f32 v[50:51], v[50:51], v[52:53]
	ds_bpermute_b32 v52, v165, v50
	ds_bpermute_b32 v53, v165, v51
	s_and_saveexec_b64 s[36:37], s[40:41]
	s_cbranch_execz .LBB0_728
	v_readlane_b32 s38, v252, 6
	v_lshlrev_b64 v[54:55], 7, v[66:67]
	v_readlane_b32 s39, v252, 7
	s_waitcnt lgkmcnt(0)
	v_pk_add_f32 v[50:51], v[50:51], v[52:53]
	v_lshl_add_u64 v[54:55], s[38:39], 0, v[54:55]
	v_lshl_add_u64 v[54:55], s[2:3], 3, v[54:55]
	global_store_dwordx2 v[54:55], v[50:51], off

;     __device__ __forceinline__ void operator()(const f32x4 (&acc)[2][2][4][2], const pg8::Unit& u, int wr, int wc, int fr, int fq, LAS unsigned char* lds, int par) const {
;     ...
;                         const int pos = row & (SEQ - 1), i0 = (c & 63) >> 1;
;                         const f32x4 r0 = *(const f32x4*)(rope + ((size_t)pos * 32 + i0) * 2), r1 = *(const f32x4*)(rope + ((size_t)pos * 32 + i0 + 2) * 2);
;                         const float sc = (kind == 1) ? 0.125f : 1.0f;
;                         f32x4 o0, o1;
;                         o0[0] = (v0[0] * r0[0] - v0[1] * r0[1]) * sc; o0[1] = (v0[1] * r0[0] + v0[0] * r0[1]) * sc;
;                         o0[2] = (v0[2] * r0[2] - v0[3] * r0[3]) * sc; o0[3] = (v0[3] * r0[2] + v0[2] * r0[3]) * sc;
;                         o1[0] = (v1[0] * r1[0] - v1[1] * r1[1]) * sc; o1[1] = (v1[1] * r1[0] + v1[0] * r1[1]) * sc;
;                         o1[2] = (v1[2] * r1[2] - v1[3] * r1[3]) * sc; o1[3] = (v1[3] * r1[2] + v1[2] * r1[3]) * sc;
;                         v0 = o0; v1 = o1;
.LBB0_738:
	s_andn2_b64 vcc, exec, s[36:37]
	s_cbranch_vccnz .LBB0_740
	s_waitcnt vmcnt(1) lgkmcnt(0)
	v_mov_b32_e32 v56, v228
	v_mov_b32_e32 v57, v229
	v_mov_b32_e32 v58, v230
	v_mov_b32_e32 v59, v231
	v_mov_b32_e32 v60, v232
	v_mov_b32_e32 v61, v233
	v_mov_b32_e32 v62, v234
	v_mov_b32_e32 v63, v235
	v_or_b32_e32 v246, v64, v178
	v_lshlrev_b32_e32 v246, 3, v246
	global_load_dwordx4 v[228:231], v246, s[12:13]
	global_load_dwordx4 v[232:235], v246, s[12:13] offset:16
	v_pk_mul_f32 v[66:67], v[46:47], v[56:57] op_sel:[1,1] op_sel_hi:[0,1]
	v_pk_fma_f32 v[68:69], v[46:47], v[56:57], v[66:67] neg_lo:[0,0,1] neg_hi:[0,0,1]
	v_pk_fma_f32 v[56:57], v[46:47], v[56:57], v[66:67] op_sel_hi:[1,0,1]
	v_mul_f32_e32 v66, v49, v59
	v_mov_b32_e32 v69, v57
	v_pk_mul_f32 v[56:57], v[148:149], v[68:69] op_sel_hi:[0,1]
	v_mul_f32_e32 v68, v49, v58
	v_pk_fma_f32 v[66:67], v[48:49], v[58:59], v[66:67] op_sel_hi:[1,1,0] neg_lo:[0,0,1] neg_hi:[0,0,1]
	v_pk_fma_f32 v[58:59], v[48:49], v[58:59], v[68:69] op_sel:[1,0,0] op_sel_hi:[0,1,0]
	v_mov_b32_e32 v67, v59
	v_pk_mul_f32 v[58:59], v[148:149], v[66:67] op_sel_hi:[0,1]
	v_pk_mul_f32 v[66:67], v[42:43], v[60:61] op_sel:[1,1] op_sel_hi:[0,1]
	v_pk_fma_f32 v[68:69], v[42:43], v[60:61], v[66:67] neg_lo:[0,0,1] neg_hi:[0,0,1]
	v_pk_fma_f32 v[60:61], v[42:43], v[60:61], v[66:67] op_sel_hi:[1,0,1]
	v_mul_f32_e32 v66, v45, v63
	v_mov_b32_e32 v69, v61
	v_pk_mul_f32 v[60:61], v[148:149], v[68:69] op_sel_hi:[0,1]
	v_mul_f32_e32 v68, v45, v62
	v_pk_fma_f32 v[66:67], v[44:45], v[62:63], v[66:67] op_sel_hi:[1,1,0] neg_lo:[0,0,1] neg_hi:[0,0,1]
	v_pk_fma_f32 v[62:63], v[44:45], v[62:63], v[68:69] op_sel:[1,0,0] op_sel_hi:[0,1,0]
	v_mov_b32_e32 v67, v63
	v_pk_mul_f32 v[62:63], v[148:149], v[66:67] op_sel_hi:[0,1]

; __device__ __forceinline__ float bf_lo(unsigned w) { return __uint_as_float(w << 16); }
; __device__ __forceinline__ float bf_hi(unsigned w) { return __uint_as_float(w & 0xffff0000u); }
; __device__ __forceinline__ u32x4 pack8(const f32x4 a, const f32x4 b) { u32x4 w; w.x = cvt_pk_bf16(a[0], a[1]); w.y = cvt_pk_bf16(a[2], a[3]); w.z = cvt_pk_bf16(b[0], b[1]); w.w = cvt_pk_bf16(b[2], b[3]); return w; }
;     __device__ __forceinline__ void operator()(const f32x4 (&acc)[2][2][4][2], const pg8::Unit& u, int wr, int wc, int fr, int fq, LAS unsigned char* lds, int par) const {
;     ...
;                     const u32x4 pw = pack8(v0, v1);
;                     *(u32x4*)(base + (size_t)row * ld + ct + c) = pw;
;                     if (kind == 0 && pn >= 4) {
;                         const float a0 = bf_lo(pw.x), a1 = bf_hi(pw.x), a2 = bf_lo(pw.y), a3 = bf_hi(pw.y), a4 = bf_lo(pw.z), a5 = bf_hi(pw.z), a6 = bf_lo(pw.w), a7 = bf_hi(pw.w);
;                         s1 += ((a0 + a1) + (a2 + a3)) + ((a4 + a5) + (a6 + a7));
;                         s2 += ((a0 * a0 + a1 * a1) + (a2 * a2 + a3 * a3)) + ((a4 * a4 + a5 * a5) + (a6 * a6 + a7 * a7));
;                     }
.LBB0_743:
	v_ashrrev_i32_e32 v51, 31, v50
	v_mul_lo_u32 v44, s29, v50
	v_mul_lo_u32 v45, s28, v51
	v_mad_u64_u32 v[42:43], s[36:37], s28, v50, 0
	v_add3_u32 v43, v43, v45, v44
	v_lshl_add_u64 v[46:47], v[42:43], 1, s[34:35]
	v_lshl_add_u64 v[46:47], v[46:47], 0, v[0:1]
	v_mov_b32_e32 v48, 0
	s_and_b64 vcc, exec, s[46:47]
	v_mov_b32_e32 v49, 0
	v_cvt_pk_bf16_f32 v42, v56, v57
	v_cvt_pk_bf16_f32 v43, v58, v59
	v_cvt_pk_bf16_f32 v44, v60, v61
	v_cvt_pk_bf16_f32 v45, v62, v63
	global_store_dwordx4 v[46:47], v[42:45], off
	s_cbranch_vccnz .LBB0_745
	v_and_b32_e32 v49, 16, v42
	v_and_b32_e32 v48, 0xffff0000, v42
	v_lshlrev_b32_e32 v59, 16, v43
	v_lshlrev_b32_e32 v58, 16, v44
	v_and_b32_e32 v56, 0xffff0000, v43
	v_mov_b32_e32 v57, v48
	v_pk_mov_b32 v[66:67], v[58:59], v[48:49] op_sel:[1,0]
	v_lshlrev_b32_e32 v42, 16, v42
	v_and_b32_e32 v60, 0xffff0000, v45
	v_mov_b32_e32 v61, v56
	v_and_b32_e32 v44, 0xffff0000, v44
	v_lshlrev_b32_e32 v62, 16, v45
	v_mov_b32_e32 v45, v59
	v_mov_b32_e32 v43, v56
	v_mov_b32_e32 v63, v56
	v_pk_add_f32 v[68:69], v[56:57], v[66:67]
	v_pk_mul_f32 v[56:57], v[56:57], v[66:67]
	v_pk_add_f32 v[48:49], v[42:43], v[48:49] op_sel_hi:[0,1]
	v_mov_b32_e32 v69, v57
	v_pk_add_f32 v[56:57], v[58:59], v[44:45]
	v_pk_mul_f32 v[66:67], v[58:59], v[58:59]
	v_mov_b32_e32 v45, v60
	v_mul_f32_e32 v49, v42, v42
	v_mov_b32_e32 v57, v67
	v_pk_add_f32 v[66:67], v[60:61], v[62:63]
	v_pk_mul_f32 v[42:43], v[60:61], v[42:43]
	v_mov_b32_e32 v59, v62
	v_pk_mul_f32 v[44:45], v[44:45], v[44:45]
	v_mov_b32_e32 v67, v43
	v_pk_fma_f32 v[44:45], v[58:59], v[58:59], v[44:45]
	v_pk_add_f32 v[48:49], v[48:49], v[68:69]
	v_pk_add_f32 v[42:43], v[56:57], v[66:67]
	v_pk_add_f32 v[44:45], v[44:45], v[44:45] op_sel_hi:[0,1]
	v_pk_add_f32 v[42:43], v[48:49], v[42:43]
	v_mov_b32_e32 v44, v1
	v_pk_add_f32 v[48:49], v[42:43], v[44:45]
	s_and_b64 vcc, exec, s[44:45]
	s_cbranch_vccnz .LBB0_747
	s_branch .LBB0_746

;     __device__ __forceinline__ void operator()(const f32x4 (&acc)[2][2][4][2], const pg8::Unit& u, int wr, int wc, int fr, int fq, LAS unsigned char* lds, int par) const {
;     ...
;                         const int pos = row & (SEQ - 1), i0 = (c & 63) >> 1;
;                         const f32x4 r0 = *(const f32x4*)(rope + ((size_t)pos * 32 + i0) * 2), r1 = *(const f32x4*)(rope + ((size_t)pos * 32 + i0 + 2) * 2);
;                         const float sc = (kind == 1) ? 0.125f : 1.0f;
;                         f32x4 o0, o1;
;                         o0[0] = (v0[0] * r0[0] - v0[1] * r0[1]) * sc; o0[1] = (v0[1] * r0[0] + v0[0] * r0[1]) * sc;
;                         o0[2] = (v0[2] * r0[2] - v0[3] * r0[3]) * sc; o0[3] = (v0[3] * r0[2] + v0[2] * r0[3]) * sc;
;                         o1[0] = (v1[0] * r1[0] - v1[1] * r1[1]) * sc; o1[1] = (v1[1] * r1[0] + v1[0] * r1[1]) * sc;
;                         o1[2] = (v1[2] * r1[2] - v1[3] * r1[3]) * sc; o1[3] = (v1[3] * r1[2] + v1[2] * r1[3]) * sc;
;                         v0 = o0; v1 = o1;
.LBB0_752:
	s_andn2_b64 vcc, exec, s[36:37]
	s_cbranch_vccnz .LBB0_754
	s_waitcnt vmcnt(1) lgkmcnt(0)
	v_mov_b32_e32 v42, v228
	v_mov_b32_e32 v43, v229
	v_mov_b32_e32 v44, v230
	v_mov_b32_e32 v45, v231
	v_mov_b32_e32 v52, v232
	v_mov_b32_e32 v53, v233
	v_mov_b32_e32 v54, v234
	v_mov_b32_e32 v55, v235
	v_add_u32_e32 v246, 0xa0, v150
	v_lshlrev_b32_e32 v246, 5, v246
	v_and_b32_e32 v246, 0x1fde0, v246
	v_lshl_or_b32 v246, v246, 3, v168
	global_load_dwordx4 v[228:231], v246, s[12:13]
	global_load_dwordx4 v[232:235], v246, s[12:13] offset:16
	v_pk_mul_f32 v[56:57], v[38:39], v[42:43] op_sel:[1,1] op_sel_hi:[0,1]
	v_pk_fma_f32 v[58:59], v[38:39], v[42:43], v[56:57] neg_lo:[0,0,1] neg_hi:[0,0,1]
	v_pk_fma_f32 v[42:43], v[38:39], v[42:43], v[56:57] op_sel_hi:[1,0,1]
	v_mul_f32_e32 v56, v41, v45
	v_mov_b32_e32 v59, v43
	v_pk_mul_f32 v[42:43], v[148:149], v[58:59] op_sel_hi:[0,1]
	v_mul_f32_e32 v58, v41, v44
	v_pk_fma_f32 v[56:57], v[40:41], v[44:45], v[56:57] op_sel_hi:[1,1,0] neg_lo:[0,0,1] neg_hi:[0,0,1]
	v_pk_fma_f32 v[44:45], v[40:41], v[44:45], v[58:59] op_sel:[1,0,0] op_sel_hi:[0,1,0]
	v_mov_b32_e32 v57, v45
	v_pk_mul_f32 v[44:45], v[148:149], v[56:57] op_sel_hi:[0,1]
	v_pk_mul_f32 v[56:57], v[34:35], v[52:53] op_sel:[1,1] op_sel_hi:[0,1]
	v_pk_fma_f32 v[58:59], v[34:35], v[52:53], v[56:57] neg_lo:[0,0,1] neg_hi:[0,0,1]
	v_pk_fma_f32 v[52:53], v[34:35], v[52:53], v[56:57] op_sel_hi:[1,0,1]
	v_mul_f32_e32 v56, v37, v55
	v_mov_b32_e32 v59, v53
	v_pk_mul_f32 v[52:53], v[148:149], v[58:59] op_sel_hi:[0,1]
	v_mul_f32_e32 v58, v37, v54
	v_pk_fma_f32 v[56:57], v[36:37], v[54:55], v[56:57] op_sel_hi:[1,1,0] neg_lo:[0,0,1] neg_hi:[0,0,1]
	v_pk_fma_f32 v[54:55], v[36:37], v[54:55], v[58:59] op_sel:[1,0,0] op_sel_hi:[0,1,0]
	v_mov_b32_e32 v57, v55
	v_pk_mul_f32 v[54:55], v[148:149], v[56:57] op_sel_hi:[0,1]

; __device__ __forceinline__ float bf_lo(unsigned w) { return __uint_as_float(w << 16); }
; __device__ __forceinline__ float bf_hi(unsigned w) { return __uint_as_float(w & 0xffff0000u); }
; __device__ __forceinline__ float shflx(float v, int k, int lane) { return __int_as_float(__builtin_amdgcn_ds_bpermute((lane ^ k) << 2, __float_as_int(v))); }
; __device__ __forceinline__ u32x4 pack8(const f32x4 a, const f32x4 b) { u32x4 w; w.x = cvt_pk_bf16(a[0], a[1]); w.y = cvt_pk_bf16(a[2], a[3]); w.z = cvt_pk_bf16(b[0], b[1]); w.w = cvt_pk_bf16(b[2], b[3]); return w; }
;     __device__ __forceinline__ void operator()(const f32x4 (&acc)[2][2][4][2], const pg8::Unit& u, int wr, int wc, int fr, int fq, LAS unsigned char* lds, int par) const {
;     ...
;                     const u32x4 pw = pack8(v0, v1);
;                     *(u32x4*)(base + (size_t)row * ld + ct + c) = pw;
;                     if (kind == 0 && pn >= 4) {
;                         const float a0 = bf_lo(pw.x), a1 = bf_hi(pw.x), a2 = bf_lo(pw.y), a3 = bf_hi(pw.y), a4 = bf_lo(pw.z), a5 = bf_hi(pw.z), a6 = bf_lo(pw.w), a7 = bf_hi(pw.w);
;                         s1 += ((a0 + a1) + (a2 + a3)) + ((a4 + a5) + (a6 + a7));
;                         s2 += ((a0 * a0 + a1 * a1) + (a2 * a2 + a3 * a3)) + ((a4 * a4 + a5 * a5) + (a6 * a6 + a7 * a7));
;                     }
;                 }
;                 if (kind == 0 && pn >= 4) {
;                     s1 += shflx(s1, 16, fr + 16 * fq); s1 += shflx(s1, 32, fr + 16 * fq); s2 += shflx(s2, 16, fr + 16 * fq); s2 += shflx(s2, 32, fr + 16 * fq);
;                     if (fq == 0) { float* sp = statsv + ((size_t)row * 16 + (pn - 4) * 4 + wc) * 2; sp[0] = s1; sp[1] = s2; }
.LBB0_757:
	s_and_b64 vcc, exec, s[46:47]
	v_cvt_pk_bf16_f32 v34, v42, v43
	v_cvt_pk_bf16_f32 v35, v44, v45
	v_cvt_pk_bf16_f32 v36, v52, v53
	v_cvt_pk_bf16_f32 v37, v54, v55
	global_store_dwordx4 v[46:47], v[34:37], off offset:16
	s_cbranch_vccnz .LBB0_761
	v_lshlrev_b32_e32 v38, 16, v34
	v_and_b32_e32 v34, 0xffff0000, v34
	v_lshlrev_b32_e32 v40, 16, v35
	v_and_b32_e32 v42, 0xffff0000, v35
	v_lshlrev_b32_e32 v44, 16, v36
	v_and_b32_e32 v36, 0xffff0000, v36
	v_lshlrev_b32_e32 v46, 16, v37
	v_and_b32_e32 v52, 0xffff0000, v37
	v_mul_f32_e32 v39, v38, v38
	v_mul_f32_e32 v35, v34, v34
	v_mul_f32_e32 v41, v40, v40
	v_mul_f32_e32 v43, v42, v42
	v_mul_f32_e32 v45, v44, v44
	v_mul_f32_e32 v37, v36, v36
	v_mul_f32_e32 v47, v46, v46
	v_mul_f32_e32 v53, v52, v52
	v_pk_add_f32 v[34:35], v[38:39], v[34:35]
	v_pk_add_f32 v[38:39], v[40:41], v[42:43]
	v_pk_add_f32 v[36:37], v[44:45], v[36:37]
	v_pk_add_f32 v[34:35], v[34:35], v[38:39]
	v_pk_add_f32 v[38:39], v[46:47], v[52:53]
	s_nop 0
	v_pk_add_f32 v[36:37], v[36:37], v[38:39]
	s_nop 0
	v_pk_add_f32 v[34:35], v[34:35], v[36:37]
	s_nop 0
	v_pk_add_f32 v[34:35], v[48:49], v[34:35]
	ds_bpermute_b32 v36, v164, v34
	ds_bpermute_b32 v37, v164, v35
	s_waitcnt lgkmcnt(0)
	v_pk_add_f32 v[34:35], v[34:35], v[36:37]
	ds_bpermute_b32 v36, v165, v34
	ds_bpermute_b32 v37, v165, v35
	s_and_saveexec_b64 s[36:37], s[40:41]
	s_cbranch_execz .LBB0_760
	v_readlane_b32 s38, v252, 6
	v_lshlrev_b64 v[38:39], 7, v[50:51]
	v_readlane_b32 s39, v252, 7
	s_waitcnt lgkmcnt(0)
	v_pk_add_f32 v[34:35], v[34:35], v[36:37]
	v_lshl_add_u64 v[38:39], s[38:39], 0, v[38:39]
	v_lshl_add_u64 v[38:39], s[2:3], 3, v[38:39]
	global_store_dwordx2 v[38:39], v[34:35], off

;     __device__ __forceinline__ void operator()(const f32x4 (&acc)[2][2][4][2], const pg8::Unit& u, int wr, int wc, int fr, int fq, LAS unsigned char* lds, int par) const {
;     ...
;                         const int pos = row & (SEQ - 1), i0 = (c & 63) >> 1;
;                         const f32x4 r0 = *(const f32x4*)(rope + ((size_t)pos * 32 + i0) * 2), r1 = *(const f32x4*)(rope + ((size_t)pos * 32 + i0 + 2) * 2);
;                         const float sc = (kind == 1) ? 0.125f : 1.0f;
;                         f32x4 o0, o1;
;                         o0[0] = (v0[0] * r0[0] - v0[1] * r0[1]) * sc; o0[1] = (v0[1] * r0[0] + v0[0] * r0[1]) * sc;
;                         o0[2] = (v0[2] * r0[2] - v0[3] * r0[3]) * sc; o0[3] = (v0[3] * r0[2] + v0[2] * r0[3]) * sc;
;                         o1[0] = (v1[0] * r1[0] - v1[1] * r1[1]) * sc; o1[1] = (v1[1] * r1[0] + v1[0] * r1[1]) * sc;
;                         o1[2] = (v1[2] * r1[2] - v1[3] * r1[3]) * sc; o1[3] = (v1[3] * r1[2] + v1[2] * r1[3]) * sc;
;                         v0 = o0; v1 = o1;
.LBB0_770:
	s_andn2_b64 vcc, exec, s[36:37]
	s_cbranch_vccnz .LBB0_772
	s_waitcnt vmcnt(1) lgkmcnt(0)
	v_mov_b32_e32 v40, v228
	v_mov_b32_e32 v41, v229
	v_mov_b32_e32 v42, v230
	v_mov_b32_e32 v43, v231
	v_mov_b32_e32 v44, v232
	v_mov_b32_e32 v45, v233
	v_mov_b32_e32 v46, v234
	v_mov_b32_e32 v47, v235
	v_or_b32_e32 v246, v48, v178
	v_lshlrev_b32_e32 v246, 3, v246
	global_load_dwordx4 v[228:231], v246, s[12:13]
	global_load_dwordx4 v[232:235], v246, s[12:13] offset:16
	v_pk_mul_f32 v[50:51], v[30:31], v[40:41] op_sel:[1,1] op_sel_hi:[0,1]
	v_pk_fma_f32 v[52:53], v[30:31], v[40:41], v[50:51] neg_lo:[0,0,1] neg_hi:[0,0,1]
	v_pk_fma_f32 v[40:41], v[30:31], v[40:41], v[50:51] op_sel_hi:[1,0,1]
	v_mul_f32_e32 v50, v33, v43
	v_mov_b32_e32 v53, v41
	v_pk_mul_f32 v[40:41], v[148:149], v[52:53] op_sel_hi:[0,1]
	v_mul_f32_e32 v52, v33, v42
	v_pk_fma_f32 v[50:51], v[32:33], v[42:43], v[50:51] op_sel_hi:[1,1,0] neg_lo:[0,0,1] neg_hi:[0,0,1]
	v_pk_fma_f32 v[42:43], v[32:33], v[42:43], v[52:53] op_sel:[1,0,0] op_sel_hi:[0,1,0]
	v_mov_b32_e32 v51, v43
	v_pk_mul_f32 v[42:43], v[148:149], v[50:51] op_sel_hi:[0,1]
	v_pk_mul_f32 v[50:51], v[26:27], v[44:45] op_sel:[1,1] op_sel_hi:[0,1]
	v_pk_fma_f32 v[52:53], v[26:27], v[44:45], v[50:51] neg_lo:[0,0,1] neg_hi:[0,0,1]
	v_pk_fma_f32 v[44:45], v[26:27], v[44:45], v[50:51] op_sel_hi:[1,0,1]
	v_mul_f32_e32 v50, v29, v47
	v_mov_b32_e32 v53, v45
	v_pk_mul_f32 v[44:45], v[148:149], v[52:53] op_sel_hi:[0,1]
	v_mul_f32_e32 v52, v29, v46
	v_pk_fma_f32 v[50:51], v[28:29], v[46:47], v[50:51] op_sel_hi:[1,1,0] neg_lo:[0,0,1] neg_hi:[0,0,1]
	v_pk_fma_f32 v[46:47], v[28:29], v[46:47], v[52:53] op_sel:[1,0,0] op_sel_hi:[0,1,0]
	v_mov_b32_e32 v51, v47
	v_pk_mul_f32 v[46:47], v[148:149], v[50:51] op_sel_hi:[0,1]

; __device__ __forceinline__ float bf_lo(unsigned w) { return __uint_as_float(w << 16); }
; __device__ __forceinline__ float bf_hi(unsigned w) { return __uint_as_float(w & 0xffff0000u); }
; __device__ __forceinline__ u32x4 pack8(const f32x4 a, const f32x4 b) { u32x4 w; w.x = cvt_pk_bf16(a[0], a[1]); w.y = cvt_pk_bf16(a[2], a[3]); w.z = cvt_pk_bf16(b[0], b[1]); w.w = cvt_pk_bf16(b[2], b[3]); return w; }
;     __device__ __forceinline__ void operator()(const f32x4 (&acc)[2][2][4][2], const pg8::Unit& u, int wr, int wc, int fr, int fq, LAS unsigned char* lds, int par) const {
;     ...
;                     const u32x4 pw = pack8(v0, v1);
;                     *(u32x4*)(base + (size_t)row * ld + ct + c) = pw;
;                     if (kind == 0 && pn >= 4) {
;                         const float a0 = bf_lo(pw.x), a1 = bf_hi(pw.x), a2 = bf_lo(pw.y), a3 = bf_hi(pw.y), a4 = bf_lo(pw.z), a5 = bf_hi(pw.z), a6 = bf_lo(pw.w), a7 = bf_hi(pw.w);
;                         s1 += ((a0 + a1) + (a2 + a3)) + ((a4 + a5) + (a6 + a7));
;                         s2 += ((a0 * a0 + a1 * a1) + (a2 * a2 + a3 * a3)) + ((a4 * a4 + a5 * a5) + (a6 * a6 + a7 * a7));
;                     }
.LBB0_775:
	v_ashrrev_i32_e32 v35, 31, v34
	v_mul_lo_u32 v28, s29, v34
	v_mul_lo_u32 v29, s28, v35
	v_mad_u64_u32 v[26:27], s[36:37], s28, v34, 0
	v_add3_u32 v27, v27, v29, v28
	v_lshl_add_u64 v[30:31], v[26:27], 1, s[34:35]
	v_lshl_add_u64 v[30:31], v[30:31], 0, v[0:1]
	v_mov_b32_e32 v32, 0
	s_and_b64 vcc, exec, s[46:47]
	v_mov_b32_e32 v33, 0
	v_cvt_pk_bf16_f32 v26, v40, v41
	v_cvt_pk_bf16_f32 v27, v42, v43
	v_cvt_pk_bf16_f32 v28, v44, v45
	v_cvt_pk_bf16_f32 v29, v46, v47
	global_store_dwordx4 v[30:31], v[26:29], off
	s_cbranch_vccnz .LBB0_777
	v_and_b32_e32 v33, 16, v26
	v_and_b32_e32 v32, 0xffff0000, v26
	v_lshlrev_b32_e32 v43, 16, v27
	v_lshlrev_b32_e32 v42, 16, v28
	v_and_b32_e32 v40, 0xffff0000, v27
	v_mov_b32_e32 v41, v32
	v_pk_mov_b32 v[50:51], v[42:43], v[32:33] op_sel:[1,0]
	v_lshlrev_b32_e32 v26, 16, v26
	v_and_b32_e32 v44, 0xffff0000, v29
	v_mov_b32_e32 v45, v40
	v_and_b32_e32 v28, 0xffff0000, v28
	v_lshlrev_b32_e32 v46, 16, v29
	v_mov_b32_e32 v29, v43
	v_mov_b32_e32 v27, v40
	v_mov_b32_e32 v47, v40
	v_pk_add_f32 v[52:53], v[40:41], v[50:51]
	v_pk_mul_f32 v[40:41], v[40:41], v[50:51]
	v_pk_add_f32 v[32:33], v[26:27], v[32:33] op_sel_hi:[0,1]
	v_mov_b32_e32 v53, v41
	v_pk_add_f32 v[40:41], v[42:43], v[28:29]
	v_pk_mul_f32 v[50:51], v[42:43], v[42:43]
	v_mov_b32_e32 v29, v44
	v_mul_f32_e32 v33, v26, v26
	v_mov_b32_e32 v41, v51
	v_pk_add_f32 v[50:51], v[44:45], v[46:47]
	v_pk_mul_f32 v[26:27], v[44:45], v[26:27]
	v_mov_b32_e32 v43, v46
	v_pk_mul_f32 v[28:29], v[28:29], v[28:29]
	v_mov_b32_e32 v51, v27
	v_pk_fma_f32 v[28:29], v[42:43], v[42:43], v[28:29]
	v_pk_add_f32 v[32:33], v[32:33], v[52:53]
	v_pk_add_f32 v[26:27], v[40:41], v[50:51]
	v_pk_add_f32 v[28:29], v[28:29], v[28:29] op_sel_hi:[0,1]
	v_pk_add_f32 v[26:27], v[32:33], v[26:27]
	v_mov_b32_e32 v28, v1
	v_pk_add_f32 v[32:33], v[26:27], v[28:29]
	s_and_b64 vcc, exec, s[44:45]
	s_cbranch_vccnz .LBB0_779
	s_branch .LBB0_778

;     __device__ __forceinline__ void operator()(const f32x4 (&acc)[2][2][4][2], const pg8::Unit& u, int wr, int wc, int fr, int fq, LAS unsigned char* lds, int par) const {
;     ...
;                         const int pos = row & (SEQ - 1), i0 = (c & 63) >> 1;
;                         const f32x4 r0 = *(const f32x4*)(rope + ((size_t)pos * 32 + i0) * 2), r1 = *(const f32x4*)(rope + ((size_t)pos * 32 + i0 + 2) * 2);
;                         const float sc = (kind == 1) ? 0.125f : 1.0f;
;                         f32x4 o0, o1;
;                         o0[0] = (v0[0] * r0[0] - v0[1] * r0[1]) * sc; o0[1] = (v0[1] * r0[0] + v0[0] * r0[1]) * sc;
;                         o0[2] = (v0[2] * r0[2] - v0[3] * r0[3]) * sc; o0[3] = (v0[3] * r0[2] + v0[2] * r0[3]) * sc;
;                         o1[0] = (v1[0] * r1[0] - v1[1] * r1[1]) * sc; o1[1] = (v1[1] * r1[0] + v1[0] * r1[1]) * sc;
;                         o1[2] = (v1[2] * r1[2] - v1[3] * r1[3]) * sc; o1[3] = (v1[3] * r1[2] + v1[2] * r1[3]) * sc;
;                         v0 = o0; v1 = o1;
.LBB0_784:
	s_andn2_b64 vcc, exec, s[36:37]
	s_cbranch_vccnz .LBB0_786
	s_waitcnt vmcnt(1) lgkmcnt(0)
	v_mov_b32_e32 v26, v228
	v_mov_b32_e32 v27, v229
	v_mov_b32_e32 v28, v230
	v_mov_b32_e32 v29, v231
	v_mov_b32_e32 v36, v232
	v_mov_b32_e32 v37, v233
	v_mov_b32_e32 v38, v234
	v_mov_b32_e32 v39, v235
	v_add_u32_e32 v246, 0xb0, v150
	v_lshlrev_b32_e32 v246, 5, v246
	v_and_b32_e32 v246, 0x1ffe0, v246
	v_lshl_or_b32 v246, v246, 3, v168
	global_load_dwordx4 v[228:231], v246, s[12:13]
	global_load_dwordx4 v[232:235], v246, s[12:13] offset:16
	v_pk_mul_f32 v[40:41], v[22:23], v[26:27] op_sel:[1,1] op_sel_hi:[0,1]
	v_pk_fma_f32 v[42:43], v[22:23], v[26:27], v[40:41] neg_lo:[0,0,1] neg_hi:[0,0,1]
	v_pk_fma_f32 v[26:27], v[22:23], v[26:27], v[40:41] op_sel_hi:[1,0,1]
	v_mul_f32_e32 v40, v25, v29
	v_mov_b32_e32 v43, v27
	v_pk_mul_f32 v[26:27], v[148:149], v[42:43] op_sel_hi:[0,1]
	v_mul_f32_e32 v42, v25, v28
	v_pk_fma_f32 v[40:41], v[24:25], v[28:29], v[40:41] op_sel_hi:[1,1,0] neg_lo:[0,0,1] neg_hi:[0,0,1]
	v_pk_fma_f32 v[28:29], v[24:25], v[28:29], v[42:43] op_sel:[1,0,0] op_sel_hi:[0,1,0]
	v_mov_b32_e32 v41, v29
	v_pk_mul_f32 v[28:29], v[148:149], v[40:41] op_sel_hi:[0,1]
	v_pk_mul_f32 v[40:41], v[18:19], v[36:37] op_sel:[1,1] op_sel_hi:[0,1]
	v_pk_fma_f32 v[42:43], v[18:19], v[36:37], v[40:41] neg_lo:[0,0,1] neg_hi:[0,0,1]
	v_pk_fma_f32 v[36:37], v[18:19], v[36:37], v[40:41] op_sel_hi:[1,0,1]
	v_mul_f32_e32 v40, v21, v39
	v_mov_b32_e32 v43, v37
	v_pk_mul_f32 v[36:37], v[148:149], v[42:43] op_sel_hi:[0,1]
	v_mul_f32_e32 v42, v21, v38
	v_pk_fma_f32 v[40:41], v[20:21], v[38:39], v[40:41] op_sel_hi:[1,1,0] neg_lo:[0,0,1] neg_hi:[0,0,1]
	v_pk_fma_f32 v[38:39], v[20:21], v[38:39], v[42:43] op_sel:[1,0,0] op_sel_hi:[0,1,0]
	v_mov_b32_e32 v41, v39
	v_pk_mul_f32 v[38:39], v[148:149], v[40:41] op_sel_hi:[0,1]

; __device__ __forceinline__ float bf_lo(unsigned w) { return __uint_as_float(w << 16); }
; __device__ __forceinline__ float bf_hi(unsigned w) { return __uint_as_float(w & 0xffff0000u); }
; __device__ __forceinline__ float shflx(float v, int k, int lane) { return __int_as_float(__builtin_amdgcn_ds_bpermute((lane ^ k) << 2, __float_as_int(v))); }
; __device__ __forceinline__ u32x4 pack8(const f32x4 a, const f32x4 b) { u32x4 w; w.x = cvt_pk_bf16(a[0], a[1]); w.y = cvt_pk_bf16(a[2], a[3]); w.z = cvt_pk_bf16(b[0], b[1]); w.w = cvt_pk_bf16(b[2], b[3]); return w; }
;     __device__ __forceinline__ void operator()(const f32x4 (&acc)[2][2][4][2], const pg8::Unit& u, int wr, int wc, int fr, int fq, LAS unsigned char* lds, int par) const {
;     ...
;                     const u32x4 pw = pack8(v0, v1);
;                     *(u32x4*)(base + (size_t)row * ld + ct + c) = pw;
;                     if (kind == 0 && pn >= 4) {
;                         const float a0 = bf_lo(pw.x), a1 = bf_hi(pw.x), a2 = bf_lo(pw.y), a3 = bf_hi(pw.y), a4 = bf_lo(pw.z), a5 = bf_hi(pw.z), a6 = bf_lo(pw.w), a7 = bf_hi(pw.w);
;                         s1 += ((a0 + a1) + (a2 + a3)) + ((a4 + a5) + (a6 + a7));
;                         s2 += ((a0 * a0 + a1 * a1) + (a2 * a2 + a3 * a3)) + ((a4 * a4 + a5 * a5) + (a6 * a6 + a7 * a7));
;                     }
;                 }
;                 if (kind == 0 && pn >= 4) {
;                     s1 += shflx(s1, 16, fr + 16 * fq); s1 += shflx(s1, 32, fr + 16 * fq); s2 += shflx(s2, 16, fr + 16 * fq); s2 += shflx(s2, 32, fr + 16 * fq);
;                     if (fq == 0) { float* sp = statsv + ((size_t)row * 16 + (pn - 4) * 4 + wc) * 2; sp[0] = s1; sp[1] = s2; }
.LBB0_789:
	s_and_b64 vcc, exec, s[46:47]
	v_cvt_pk_bf16_f32 v18, v26, v27
	v_cvt_pk_bf16_f32 v19, v28, v29
	v_cvt_pk_bf16_f32 v20, v36, v37
	v_cvt_pk_bf16_f32 v21, v38, v39
	global_store_dwordx4 v[30:31], v[18:21], off offset:16
	s_cbranch_vccnz .LBB0_793
	v_lshlrev_b32_e32 v22, 16, v18
	v_and_b32_e32 v18, 0xffff0000, v18
	v_lshlrev_b32_e32 v24, 16, v19
	v_and_b32_e32 v26, 0xffff0000, v19
	v_lshlrev_b32_e32 v28, 16, v20
	v_and_b32_e32 v20, 0xffff0000, v20
	v_lshlrev_b32_e32 v30, 16, v21
	v_and_b32_e32 v36, 0xffff0000, v21
	v_mul_f32_e32 v23, v22, v22
	v_mul_f32_e32 v19, v18, v18
	v_mul_f32_e32 v25, v24, v24
	v_mul_f32_e32 v27, v26, v26
	v_mul_f32_e32 v29, v28, v28
	v_mul_f32_e32 v21, v20, v20
	v_mul_f32_e32 v31, v30, v30
	v_mul_f32_e32 v37, v36, v36
	v_pk_add_f32 v[18:19], v[22:23], v[18:19]
	v_pk_add_f32 v[22:23], v[24:25], v[26:27]
	v_pk_add_f32 v[20:21], v[28:29], v[20:21]
	v_pk_add_f32 v[18:19], v[18:19], v[22:23]
	v_pk_add_f32 v[22:23], v[30:31], v[36:37]
	s_nop 0
	v_pk_add_f32 v[20:21], v[20:21], v[22:23]
	s_nop 0
	v_pk_add_f32 v[18:19], v[18:19], v[20:21]
	s_nop 0
	v_pk_add_f32 v[18:19], v[32:33], v[18:19]
	ds_bpermute_b32 v20, v164, v18
	ds_bpermute_b32 v21, v164, v19
	s_waitcnt lgkmcnt(0)
	v_pk_add_f32 v[18:19], v[18:19], v[20:21]
	ds_bpermute_b32 v20, v165, v18
	ds_bpermute_b32 v21, v165, v19
	s_and_saveexec_b64 s[36:37], s[40:41]
	s_cbranch_execz .LBB0_792
	v_readlane_b32 s38, v252, 6
	v_lshlrev_b64 v[22:23], 7, v[34:35]
	v_readlane_b32 s39, v252, 7
	s_waitcnt lgkmcnt(0)
	v_pk_add_f32 v[18:19], v[18:19], v[20:21]
	v_lshl_add_u64 v[22:23], s[38:39], 0, v[22:23]
	v_lshl_add_u64 v[22:23], s[2:3], 3, v[22:23]
	global_store_dwordx2 v[22:23], v[18:19], off

;     __device__ __forceinline__ void operator()(const f32x4 (&acc)[2][2][4][2], const pg8::Unit& u, int wr, int wc, int fr, int fq, LAS unsigned char* lds, int par) const {
;     ...
;                         const int pos = row & (SEQ - 1), i0 = (c & 63) >> 1;
;                         const f32x4 r0 = *(const f32x4*)(rope + ((size_t)pos * 32 + i0) * 2), r1 = *(const f32x4*)(rope + ((size_t)pos * 32 + i0 + 2) * 2);
;                         const float sc = (kind == 1) ? 0.125f : 1.0f;
;                         f32x4 o0, o1;
;                         o0[0] = (v0[0] * r0[0] - v0[1] * r0[1]) * sc; o0[1] = (v0[1] * r0[0] + v0[0] * r0[1]) * sc;
;                         o0[2] = (v0[2] * r0[2] - v0[3] * r0[3]) * sc; o0[3] = (v0[3] * r0[2] + v0[2] * r0[3]) * sc;
;                         o1[0] = (v1[0] * r1[0] - v1[1] * r1[1]) * sc; o1[1] = (v1[1] * r1[0] + v1[0] * r1[1]) * sc;
;                         o1[2] = (v1[2] * r1[2] - v1[3] * r1[3]) * sc; o1[3] = (v1[3] * r1[2] + v1[2] * r1[3]) * sc;
;                         v0 = o0; v1 = o1;
.LBB0_802:
	s_andn2_b64 vcc, exec, s[36:37]
	s_cbranch_vccnz .LBB0_804
	s_waitcnt vmcnt(1) lgkmcnt(0)
	v_mov_b32_e32 v24, v228
	v_mov_b32_e32 v25, v229
	v_mov_b32_e32 v26, v230
	v_mov_b32_e32 v27, v231
	v_mov_b32_e32 v28, v232
	v_mov_b32_e32 v29, v233
	v_mov_b32_e32 v30, v234
	v_mov_b32_e32 v31, v235
	v_or_b32_e32 v246, v32, v178
	v_lshlrev_b32_e32 v246, 3, v246
	global_load_dwordx4 v[228:231], v246, s[12:13]
	global_load_dwordx4 v[232:235], v246, s[12:13] offset:16
	v_pk_mul_f32 v[34:35], v[14:15], v[24:25] op_sel:[1,1] op_sel_hi:[0,1]
	v_pk_fma_f32 v[36:37], v[14:15], v[24:25], v[34:35] neg_lo:[0,0,1] neg_hi:[0,0,1]
	v_pk_fma_f32 v[24:25], v[14:15], v[24:25], v[34:35] op_sel_hi:[1,0,1]
	v_mul_f32_e32 v34, v17, v27
	v_mov_b32_e32 v37, v25
	v_pk_mul_f32 v[24:25], v[148:149], v[36:37] op_sel_hi:[0,1]
	v_mul_f32_e32 v36, v17, v26
	v_pk_fma_f32 v[34:35], v[16:17], v[26:27], v[34:35] op_sel_hi:[1,1,0] neg_lo:[0,0,1] neg_hi:[0,0,1]
	v_pk_fma_f32 v[26:27], v[16:17], v[26:27], v[36:37] op_sel:[1,0,0] op_sel_hi:[0,1,0]
	v_mov_b32_e32 v35, v27
	v_pk_mul_f32 v[26:27], v[148:149], v[34:35] op_sel_hi:[0,1]
	v_pk_mul_f32 v[34:35], v[10:11], v[28:29] op_sel:[1,1] op_sel_hi:[0,1]
	v_pk_fma_f32 v[36:37], v[10:11], v[28:29], v[34:35] neg_lo:[0,0,1] neg_hi:[0,0,1]
	v_pk_fma_f32 v[28:29], v[10:11], v[28:29], v[34:35] op_sel_hi:[1,0,1]
	v_mul_f32_e32 v34, v13, v31
	v_mov_b32_e32 v37, v29
	v_pk_mul_f32 v[28:29], v[148:149], v[36:37] op_sel_hi:[0,1]
	v_mul_f32_e32 v36, v13, v30
	v_pk_fma_f32 v[34:35], v[12:13], v[30:31], v[34:35] op_sel_hi:[1,1,0] neg_lo:[0,0,1] neg_hi:[0,0,1]
	v_pk_fma_f32 v[30:31], v[12:13], v[30:31], v[36:37] op_sel:[1,0,0] op_sel_hi:[0,1,0]
	v_mov_b32_e32 v35, v31
	v_pk_mul_f32 v[30:31], v[148:149], v[34:35] op_sel_hi:[0,1]

; __device__ __forceinline__ float bf_lo(unsigned w) { return __uint_as_float(w << 16); }
; __device__ __forceinline__ float bf_hi(unsigned w) { return __uint_as_float(w & 0xffff0000u); }
; __device__ __forceinline__ u32x4 pack8(const f32x4 a, const f32x4 b) { u32x4 w; w.x = cvt_pk_bf16(a[0], a[1]); w.y = cvt_pk_bf16(a[2], a[3]); w.z = cvt_pk_bf16(b[0], b[1]); w.w = cvt_pk_bf16(b[2], b[3]); return w; }
;     __device__ __forceinline__ void operator()(const f32x4 (&acc)[2][2][4][2], const pg8::Unit& u, int wr, int wc, int fr, int fq, LAS unsigned char* lds, int par) const {
;     ...
;                     const u32x4 pw = pack8(v0, v1);
;                     *(u32x4*)(base + (size_t)row * ld + ct + c) = pw;
;                     if (kind == 0 && pn >= 4) {
;                         const float a0 = bf_lo(pw.x), a1 = bf_hi(pw.x), a2 = bf_lo(pw.y), a3 = bf_hi(pw.y), a4 = bf_lo(pw.z), a5 = bf_hi(pw.z), a6 = bf_lo(pw.w), a7 = bf_hi(pw.w);
;                         s1 += ((a0 + a1) + (a2 + a3)) + ((a4 + a5) + (a6 + a7));
;                         s2 += ((a0 * a0 + a1 * a1) + (a2 * a2 + a3 * a3)) + ((a4 * a4 + a5 * a5) + (a6 * a6 + a7 * a7));
;                     }
.LBB0_807:
	v_ashrrev_i32_e32 v19, 31, v18
	v_mul_lo_u32 v12, s29, v18
	v_mul_lo_u32 v13, s28, v19
	v_mad_u64_u32 v[10:11], s[28:29], s28, v18, 0
	v_add3_u32 v11, v11, v13, v12
	v_lshl_add_u64 v[14:15], v[10:11], 1, s[34:35]
	v_lshl_add_u64 v[14:15], v[14:15], 0, v[0:1]
	v_mov_b32_e32 v16, 0
	s_and_b64 vcc, exec, s[46:47]
	v_mov_b32_e32 v17, 0
	v_cvt_pk_bf16_f32 v10, v24, v25
	v_cvt_pk_bf16_f32 v11, v26, v27
	v_cvt_pk_bf16_f32 v12, v28, v29
	v_cvt_pk_bf16_f32 v13, v30, v31
	global_store_dwordx4 v[14:15], v[10:13], off
	s_cbranch_vccnz .LBB0_809
	v_and_b32_e32 v17, 16, v10
	v_and_b32_e32 v16, 0xffff0000, v10
	v_lshlrev_b32_e32 v0, 16, v10
	v_and_b32_e32 v24, 0xffff0000, v11
	v_lshlrev_b32_e32 v11, 16, v11
	v_lshlrev_b32_e32 v10, 16, v12
	v_mov_b32_e32 v25, v16
	v_pk_mov_b32 v[30:31], v[10:11], v[16:17] op_sel:[1,0]
	v_and_b32_e32 v26, 0xffff0000, v13
	v_mov_b32_e32 v27, v24
	v_and_b32_e32 v12, 0xffff0000, v12
	v_lshlrev_b32_e32 v28, 16, v13
	v_mov_b32_e32 v13, v11
	v_mov_b32_e32 v33, v24
	v_mov_b32_e32 v29, v24
	v_pk_add_f32 v[16:17], v[0:1], v[16:17] op_sel_hi:[0,1]
	v_pk_add_f32 v[34:35], v[24:25], v[30:31]
	v_pk_mul_f32 v[24:25], v[24:25], v[30:31]
	v_mul_f32_e32 v17, v0, v0
	v_mov_b32_e32 v35, v25
	v_pk_add_f32 v[24:25], v[10:11], v[12:13]
	v_pk_mul_f32 v[30:31], v[10:11], v[10:11]
	v_mov_b32_e32 v13, v26
	v_pk_add_f32 v[16:17], v[16:17], v[34:35]
	v_mov_b32_e32 v25, v31
	v_pk_add_f32 v[30:31], v[26:27], v[28:29]
	v_pk_mul_f32 v[34:35], v[26:27], v[32:33]
	v_mov_b32_e32 v11, v28
	v_pk_mul_f32 v[12:13], v[12:13], v[12:13]
	v_mov_b32_e32 v31, v35
	v_pk_fma_f32 v[10:11], v[10:11], v[10:11], v[12:13]
	v_pk_add_f32 v[24:25], v[24:25], v[30:31]
	v_pk_add_f32 v[10:11], v[10:11], v[10:11] op_sel_hi:[0,1]
	v_pk_add_f32 v[16:17], v[16:17], v[24:25]
	v_mov_b32_e32 v10, v1
	v_pk_add_f32 v[16:17], v[16:17], v[10:11]
	s_and_b64 vcc, exec, s[44:45]
	s_cbranch_vccnz .LBB0_811
	s_branch .LBB0_810

;     __device__ __forceinline__ void operator()(const f32x4 (&acc)[2][2][4][2], const pg8::Unit& u, int wr, int wc, int fr, int fq, LAS unsigned char* lds, int par) const {
;     ...
;                         const int pos = row & (SEQ - 1), i0 = (c & 63) >> 1;
;                         const f32x4 r0 = *(const f32x4*)(rope + ((size_t)pos * 32 + i0) * 2), r1 = *(const f32x4*)(rope + ((size_t)pos * 32 + i0 + 2) * 2);
;                         const float sc = (kind == 1) ? 0.125f : 1.0f;
;                         f32x4 o0, o1;
;                         o0[0] = (v0[0] * r0[0] - v0[1] * r0[1]) * sc; o0[1] = (v0[1] * r0[0] + v0[0] * r0[1]) * sc;
;                         o0[2] = (v0[2] * r0[2] - v0[3] * r0[3]) * sc; o0[3] = (v0[3] * r0[2] + v0[2] * r0[3]) * sc;
;                         o1[0] = (v1[0] * r1[0] - v1[1] * r1[1]) * sc; o1[1] = (v1[1] * r1[0] + v1[0] * r1[1]) * sc;
;                         o1[2] = (v1[2] * r1[2] - v1[3] * r1[3]) * sc; o1[3] = (v1[3] * r1[2] + v1[2] * r1[3]) * sc;
;                         v0 = o0; v1 = o1;
.LBB0_816:
	s_andn2_b64 vcc, exec, s[28:29]
	s_cbranch_vccnz .LBB0_818
	s_waitcnt vmcnt(1) lgkmcnt(0)
	v_mov_b32_e32 v10, v228
	v_mov_b32_e32 v11, v229
	v_mov_b32_e32 v12, v230
	v_mov_b32_e32 v13, v231
	v_mov_b32_e32 v20, v232
	v_mov_b32_e32 v21, v233
	v_mov_b32_e32 v22, v234
	v_mov_b32_e32 v23, v235
	v_pk_mul_f32 v[24:25], v[6:7], v[10:11] op_sel:[1,1] op_sel_hi:[0,1]
	v_mul_f32_e32 v0, v9, v13
	v_pk_fma_f32 v[26:27], v[6:7], v[10:11], v[24:25] neg_lo:[0,0,1] neg_hi:[0,0,1]
	v_pk_fma_f32 v[10:11], v[6:7], v[10:11], v[24:25] op_sel_hi:[1,0,1]
	v_pk_fma_f32 v[24:25], v[8:9], v[12:13], v[0:1] op_sel_hi:[1,1,0] neg_lo:[0,0,1] neg_hi:[0,0,1]
	v_mul_f32_e32 v0, v9, v12
	v_pk_fma_f32 v[12:13], v[8:9], v[12:13], v[0:1] op_sel:[1,0,0] op_sel_hi:[0,1,0]
	v_mov_b32_e32 v25, v13
	v_mov_b32_e32 v27, v11
	v_pk_mul_f32 v[12:13], v[148:149], v[24:25] op_sel_hi:[0,1]
	v_pk_mul_f32 v[24:25], v[2:3], v[20:21] op_sel:[1,1] op_sel_hi:[0,1]
	v_mul_f32_e32 v0, v5, v23
	v_pk_mul_f32 v[10:11], v[148:149], v[26:27] op_sel_hi:[0,1]
	v_pk_fma_f32 v[26:27], v[2:3], v[20:21], v[24:25] neg_lo:[0,0,1] neg_hi:[0,0,1]
	v_pk_fma_f32 v[20:21], v[2:3], v[20:21], v[24:25] op_sel_hi:[1,0,1]
	v_pk_fma_f32 v[24:25], v[4:5], v[22:23], v[0:1] op_sel_hi:[1,1,0] neg_lo:[0,0,1] neg_hi:[0,0,1]
	v_mul_f32_e32 v0, v5, v22
	v_pk_fma_f32 v[22:23], v[4:5], v[22:23], v[0:1] op_sel:[1,0,0] op_sel_hi:[0,1,0]
	v_mov_b32_e32 v27, v21
	v_mov_b32_e32 v25, v23
	v_pk_mul_f32 v[20:21], v[148:149], v[26:27] op_sel_hi:[0,1]
	v_pk_mul_f32 v[22:23], v[148:149], v[24:25] op_sel_hi:[0,1]

; __device__ __forceinline__ float bf_lo(unsigned w) { return __uint_as_float(w << 16); }
; __device__ __forceinline__ float bf_hi(unsigned w) { return __uint_as_float(w & 0xffff0000u); }
; __device__ __forceinline__ float shflx(float v, int k, int lane) { return __int_as_float(__builtin_amdgcn_ds_bpermute((lane ^ k) << 2, __float_as_int(v))); }
; __device__ __forceinline__ u32x4 pack8(const f32x4 a, const f32x4 b) { u32x4 w; w.x = cvt_pk_bf16(a[0], a[1]); w.y = cvt_pk_bf16(a[2], a[3]); w.z = cvt_pk_bf16(b[0], b[1]); w.w = cvt_pk_bf16(b[2], b[3]); return w; }
;     __device__ __forceinline__ void operator()(const f32x4 (&acc)[2][2][4][2], const pg8::Unit& u, int wr, int wc, int fr, int fq, LAS unsigned char* lds, int par) const {
;     ...
;                     const u32x4 pw = pack8(v0, v1);
;                     *(u32x4*)(base + (size_t)row * ld + ct + c) = pw;
;                     if (kind == 0 && pn >= 4) {
;                         const float a0 = bf_lo(pw.x), a1 = bf_hi(pw.x), a2 = bf_lo(pw.y), a3 = bf_hi(pw.y), a4 = bf_lo(pw.z), a5 = bf_hi(pw.z), a6 = bf_lo(pw.w), a7 = bf_hi(pw.w);
;                         s1 += ((a0 + a1) + (a2 + a3)) + ((a4 + a5) + (a6 + a7));
;                         s2 += ((a0 * a0 + a1 * a1) + (a2 * a2 + a3 * a3)) + ((a4 * a4 + a5 * a5) + (a6 * a6 + a7 * a7));
;                     }
;                 }
;                 if (kind == 0 && pn >= 4) {
;                     s1 += shflx(s1, 16, fr + 16 * fq); s1 += shflx(s1, 32, fr + 16 * fq); s2 += shflx(s2, 16, fr + 16 * fq); s2 += shflx(s2, 32, fr + 16 * fq);
;                     if (fq == 0) { float* sp = statsv + ((size_t)row * 16 + (pn - 4) * 4 + wc) * 2; sp[0] = s1; sp[1] = s2; }
.LBB0_821:
	s_and_b64 vcc, exec, s[46:47]
	v_cvt_pk_bf16_f32 v2, v10, v11
	v_cvt_pk_bf16_f32 v3, v12, v13
	v_cvt_pk_bf16_f32 v4, v20, v21
	v_cvt_pk_bf16_f32 v5, v22, v23
	global_store_dwordx4 v[14:15], v[2:5], off offset:16
	s_cbranch_vccnz .LBB0_825
	v_lshlrev_b32_e32 v6, 16, v2
	v_and_b32_e32 v2, 0xffff0000, v2
	v_lshlrev_b32_e32 v8, 16, v3
	v_and_b32_e32 v10, 0xffff0000, v3
	v_lshlrev_b32_e32 v12, 16, v4
	v_and_b32_e32 v4, 0xffff0000, v4
	v_lshlrev_b32_e32 v14, 16, v5
	v_and_b32_e32 v20, 0xffff0000, v5
	v_mul_f32_e32 v7, v6, v6
	v_mul_f32_e32 v3, v2, v2
	v_mul_f32_e32 v9, v8, v8
	v_mul_f32_e32 v11, v10, v10
	v_mul_f32_e32 v13, v12, v12
	v_mul_f32_e32 v5, v4, v4
	v_mul_f32_e32 v15, v14, v14
	v_mul_f32_e32 v21, v20, v20
	v_pk_add_f32 v[2:3], v[6:7], v[2:3]
	v_pk_add_f32 v[6:7], v[8:9], v[10:11]
	v_pk_add_f32 v[4:5], v[12:13], v[4:5]
	v_pk_add_f32 v[2:3], v[2:3], v[6:7]
	v_pk_add_f32 v[6:7], v[14:15], v[20:21]
	s_nop 0
	v_pk_add_f32 v[4:5], v[4:5], v[6:7]
	s_nop 0
	v_pk_add_f32 v[2:3], v[2:3], v[4:5]
	s_nop 0
	v_pk_add_f32 v[2:3], v[16:17], v[2:3]
	ds_bpermute_b32 v4, v164, v2
	ds_bpermute_b32 v5, v164, v3
	s_waitcnt lgkmcnt(0)
	v_pk_add_f32 v[2:3], v[2:3], v[4:5]
	ds_bpermute_b32 v4, v165, v2
	ds_bpermute_b32 v5, v165, v3
	s_and_saveexec_b64 s[26:27], s[40:41]
	s_cbranch_execz .LBB0_824
	v_readlane_b32 s28, v252, 6
	v_lshlrev_b64 v[6:7], 7, v[18:19]
	v_readlane_b32 s29, v252, 7
	s_waitcnt lgkmcnt(0)
	v_pk_add_f32 v[2:3], v[2:3], v[4:5]
	v_lshl_add_u64 v[6:7], s[28:29], 0, v[6:7]
	v_lshl_add_u64 v[6:7], s[2:3], 3, v[6:7]
	global_store_dwordx2 v[6:7], v[2:3], off
